# v30 (attn A packed row-sum, SwiGLU exp-negate peephole) plus attn C exp reorder removing 6 copy movs
# speedup vs baseline: 1.0047x; 1.0047x over previous
.LBB0_753:
	v_exp_f32_e32 v112, v112
	v_exp_f32_e32 v113, v113
	v_exp_f32_e32 v114, v114
	v_exp_f32_e32 v115, v115
	v_exp_f32_e32 v116, v116
	v_exp_f32_e32 v117, v117
	v_exp_f32_e32 v118, v118
	v_exp_f32_e32 v119, v119
	ds_read_b64_tr_b16 v[136:137], v207 offset:55296
	ds_read_b64_tr_b16 v[138:139], v207 offset:57856
	ds_read_b64_tr_b16 v[140:141], v207 offset:55360
	ds_read_b64_tr_b16 v[144:145], v207 offset:55424
	ds_read_b64_tr_b16 v[148:149], v207 offset:55488
	ds_read_b64_tr_b16 v[142:143], v207 offset:57920
	ds_read_b64_tr_b16 v[146:147], v207 offset:57984
	ds_read_b64_tr_b16 v[150:151], v207 offset:58048
	v_cvt_pk_bf16_f32 v132, v112, v113
	v_cvt_pk_bf16_f32 v133, v114, v115
	v_cvt_pk_bf16_f32 v134, v116, v117
	v_cvt_pk_bf16_f32 v135, v118, v119
	v_exp_f32_e32 v129, v121
	s_waitcnt lgkmcnt(6)
	v_mfma_f32_32x32x16_bf16 v[48:63], v[136:139], v[132:135], v[48:63]
	v_exp_f32_e32 v130, v123
	v_exp_f32_e32 v121, v122
	v_exp_f32_e32 v122, v124
	v_exp_f32_e32 v124, v125
	s_waitcnt lgkmcnt(2)
	v_mfma_f32_32x32x16_bf16 v[32:47], v[140:143], v[132:135], v[32:47]
	v_exp_f32_e32 v120, v120
	v_exp_f32_e32 v123, v126
	v_exp_f32_e32 v125, v127
	s_waitcnt lgkmcnt(1)
	v_mfma_f32_32x32x16_bf16 v[16:31], v[144:147], v[132:135], v[16:31]
	ds_read_b64_tr_b16 v[140:141], v207 offset:60416
	ds_read_b64_tr_b16 v[142:143], v207 offset:62976
	v_cvt_pk_bf16_f32 v136, v120, v129
	v_cvt_pk_bf16_f32 v137, v121, v130
	v_cvt_pk_bf16_f32 v138, v122, v124
	v_cvt_pk_bf16_f32 v139, v123, v125
	v_exp_f32_e32 v126, v97
	s_waitcnt lgkmcnt(2)
	v_mfma_f32_32x32x16_bf16 v[0:15], v[148:151], v[132:135], v[0:15]
	ds_read_b64_tr_b16 v[132:133], v207 offset:60480
	ds_read_b64_tr_b16 v[144:145], v207 offset:60544
	ds_read_b64_tr_b16 v[148:149], v207 offset:60608
	ds_read_b64_tr_b16 v[134:135], v207 offset:63040
	ds_read_b64_tr_b16 v[146:147], v207 offset:63104
	ds_read_b64_tr_b16 v[150:151], v207 offset:63168
	v_exp_f32_e32 v127, v99
	v_exp_f32_e32 v97, v98
	v_exp_f32_e32 v98, v100
	s_waitcnt lgkmcnt(6)
	v_mfma_f32_32x32x16_bf16 v[48:63], v[140:143], v[136:139], v[48:63]
	v_exp_f32_e32 v100, v101
	v_exp_f32_e32 v96, v96
	v_exp_f32_e32 v99, v102
	s_waitcnt lgkmcnt(2)
	v_mfma_f32_32x32x16_bf16 v[32:47], v[132:135], v[136:139], v[32:47]
	v_exp_f32_e32 v101, v103
	ds_read_b64_tr_b16 v[140:141], v209 offset:10240
	ds_read_b64_tr_b16 v[142:143], v209 offset:12800
	v_cvt_pk_bf16_f32 v132, v96, v126
	v_cvt_pk_bf16_f32 v133, v97, v127
	v_cvt_pk_bf16_f32 v134, v98, v100
	v_cvt_pk_bf16_f32 v135, v99, v101
	s_waitcnt lgkmcnt(3)
	v_mfma_f32_32x32x16_bf16 v[16:31], v[144:147], v[136:139], v[16:31]
	v_exp_f32_e32 v102, v104
	v_exp_f32_e32 v104, v105
	v_exp_f32_e32 v107, v107
	v_exp_f32_e32 v105, v108
	s_waitcnt lgkmcnt(2)
	v_mfma_f32_32x32x16_bf16 v[0:15], v[148:151], v[136:139], v[0:15]
	ds_read_b64_tr_b16 v[136:137], v209 offset:10304
	ds_read_b64_tr_b16 v[144:145], v209 offset:10368
	ds_read_b64_tr_b16 v[148:149], v209 offset:10432
	ds_read_b64_tr_b16 v[138:139], v209 offset:12864
	ds_read_b64_tr_b16 v[146:147], v209 offset:12928
	ds_read_b64_tr_b16 v[150:151], v209 offset:12992
	v_exp_f32_e32 v108, v109
	v_exp_f32_e32 v103, v106
	s_waitcnt lgkmcnt(6)
	v_mfma_f32_32x32x16_bf16 v[48:63], v[140:143], v[132:135], v[48:63]
	v_exp_f32_e32 v106, v110
	v_exp_f32_e32 v109, v111
	ds_read_b64_tr_b16 v[140:141], v209 offset:15360
	ds_read_b64_tr_b16 v[142:143], v209 offset:17920
	s_andn2_b64 vcc, exec, s[20:21]
	s_waitcnt lgkmcnt(4)
	v_mfma_f32_32x32x16_bf16 v[32:47], v[136:139], v[132:135], v[32:47]
	v_cvt_pk_bf16_f32 v136, v102, v104
	v_cvt_pk_bf16_f32 v137, v103, v107
	v_cvt_pk_bf16_f32 v138, v105, v108
	v_cvt_pk_bf16_f32 v139, v106, v109
	s_waitcnt lgkmcnt(3)
	v_mfma_f32_32x32x16_bf16 v[16:31], v[144:147], v[132:135], v[16:31]
	s_waitcnt lgkmcnt(2)
	v_mfma_f32_32x32x16_bf16 v[0:15], v[148:151], v[132:135], v[0:15]
	ds_read_b64_tr_b16 v[132:133], v209 offset:15424
	ds_read_b64_tr_b16 v[144:145], v209 offset:15488
	ds_read_b64_tr_b16 v[148:149], v209 offset:15552
	ds_read_b64_tr_b16 v[134:135], v209 offset:17984
	ds_read_b64_tr_b16 v[146:147], v209 offset:18048
	ds_read_b64_tr_b16 v[150:151], v209 offset:18112
	s_waitcnt lgkmcnt(6)
	v_mfma_f32_32x32x16_bf16 v[48:63], v[140:143], v[136:139], v[48:63]
	s_waitcnt lgkmcnt(2)
	v_mfma_f32_32x32x16_bf16 v[32:47], v[132:135], v[136:139], v[32:47]
	s_waitcnt lgkmcnt(1)
	v_mfma_f32_32x32x16_bf16 v[16:31], v[144:147], v[136:139], v[16:31]
	s_waitcnt lgkmcnt(0)
	v_mfma_f32_32x32x16_bf16 v[0:15], v[148:151], v[136:139], v[0:15]
	s_cbranch_vccnz .LBB0_755
	s_waitcnt vmcnt(1)
	ds_write_b128 v241, v[176:179] offset:17408
	s_waitcnt vmcnt(0)
	ds_write_b128 v242, v[180:183] offset:17408

.LBB0_774:
	v_pk_add_f32 v[78:79], v[80:81], v[78:79]
	v_pk_add_f32 v[66:67], v[70:71], v[66:67]
	v_pk_add_f32 v[78:79], v[82:83], v[78:79]
	v_pk_add_f32 v[66:67], v[72:73], v[66:67]
	v_pk_add_f32 v[78:79], v[84:85], v[78:79]
	v_pk_add_f32 v[66:67], v[74:75], v[66:67]
	v_pk_add_f32 v[78:79], v[86:87], v[78:79]
	v_pk_add_f32 v[66:67], v[76:77], v[66:67]
	v_pk_add_f32 v[78:79], v[88:89], v[78:79]
	v_pk_add_f32 v[78:79], v[90:91], v[78:79]
	v_pk_add_f32 v[78:79], v[92:93], v[78:79]
	v_pk_add_f32 v[78:79], v[94:95], v[78:79]
	v_pk_add_f32 v[78:79], v[96:97], v[78:79]
	v_pk_add_f32 v[66:67], v[78:79], v[66:67]
	v_add_f32_e32 v66, v66, v67
	v_add_f32_e32 v66, v69, v66
	v_add_f32_e32 v66, v98, v66
	s_add_i32 s26, s26, 2
	v_add_f32_e32 v0, v0, v66
	v_lshl_add_u64 v[168:169], v[168:169], 0, s[16:17]
	v_add_u32_e32 v191, 0x80, v191
	v_lshl_add_u64 v[170:171], v[170:171], 0, s[16:17]
	s_cmp_lt_u32 s42, s43
	v_lshl_add_u64 v[172:173], v[172:173], 0, s[16:17]
	s_waitcnt lgkmcnt(0)
	s_barrier
	s_cbranch_scc0 .LBB0_793

.LBB0_786:
	v_pk_add_f32 v[98:99], v[100:101], v[98:99]
	v_pk_add_f32 v[114:115], v[116:117], v[114:115]
	v_pk_add_f32 v[98:99], v[102:103], v[98:99]
	v_pk_add_f32 v[114:115], v[118:119], v[114:115]
	v_pk_add_f32 v[98:99], v[104:105], v[98:99]
	v_pk_add_f32 v[114:115], v[120:121], v[114:115]
	v_pk_add_f32 v[98:99], v[106:107], v[98:99]
	v_pk_add_f32 v[114:115], v[122:123], v[114:115]
	v_pk_add_f32 v[98:99], v[108:109], v[98:99]
	v_pk_add_f32 v[114:115], v[124:125], v[114:115]
	v_pk_add_f32 v[98:99], v[110:111], v[98:99]
	v_pk_add_f32 v[114:115], v[126:127], v[114:115]
	v_pk_add_f32 v[98:99], v[112:113], v[98:99]
	v_pk_add_f32 v[114:115], v[128:129], v[114:115]
	v_add_f32_e32 v98, v98, v99
	v_add_f32_e32 v99, v114, v115
	v_add_f32_e32 v98, v98, v99
	v_add_f32_e32 v0, v0, v98
	v_add_u32_e32 v98, 64, v191
	v_cmp_lt_u32_e32 vcc, s29, v98
	s_nop 1
	v_cndmask_b32_e32 v98, v176, v66, vcc
	v_add_u32_e32 v66, 0x60, v191
	v_cmp_lt_u32_e32 vcc, s29, v66
	v_add_u32_e32 v66, 0x41, v191
	s_nop 0
	v_cndmask_b32_e32 v82, v176, v82, vcc
	v_cmp_lt_u32_e32 vcc, s29, v66
	v_add_u32_e32 v66, 0x61, v191
	s_nop 0
	v_cndmask_b32_e32 v99, v176, v67, vcc
	v_cmp_lt_u32_e32 vcc, s29, v66
	v_add_u32_e32 v66, 0x42, v191
	v_add_u32_e32 v67, 0x5a, v191
	v_cndmask_b32_e32 v83, v176, v83, vcc
	v_cmp_lt_u32_e32 vcc, s29, v66
	v_add_u32_e32 v66, 0x62, v191
	s_nop 0
	v_cndmask_b32_e32 v100, v176, v68, vcc
	v_cmp_lt_u32_e32 vcc, s29, v66
	v_add_u32_e32 v66, 0x43, v191
	v_add_u32_e32 v68, 0x5b, v191
	v_cndmask_b32_e32 v84, v176, v84, vcc
	v_cmp_lt_u32_e32 vcc, s29, v66
	v_add_u32_e32 v66, 0x63, v191
	s_nop 0
	v_cndmask_b32_e32 v101, v176, v69, vcc
	v_cmp_lt_u32_e32 vcc, s29, v66
	v_add_u32_e32 v66, 0x48, v191
	s_nop 0
	v_cndmask_b32_e32 v85, v176, v85, vcc
	v_cmp_lt_u32_e32 vcc, s29, v66
	v_add_u32_e32 v66, 0x68, v191
	s_nop 0
	v_cndmask_b32_e32 v102, v176, v70, vcc
	v_cmp_lt_u32_e32 vcc, s29, v66
	v_add_u32_e32 v66, 0x49, v191
	s_nop 0
	v_cndmask_b32_e32 v86, v176, v86, vcc
	v_cmp_lt_u32_e32 vcc, s29, v66
	v_add_u32_e32 v66, 0x69, v191
	s_nop 0
	v_cndmask_b32_e32 v103, v176, v71, vcc
	v_cmp_lt_u32_e32 vcc, s29, v66
	v_add_u32_e32 v66, 0x4a, v191
	s_nop 0
	v_cndmask_b32_e32 v87, v176, v87, vcc
	v_cmp_lt_u32_e32 vcc, s29, v66
	v_add_u32_e32 v66, 0x6a, v191
	s_nop 0
	v_cndmask_b32_e32 v104, v176, v72, vcc
	v_cmp_lt_u32_e32 vcc, s29, v66
	v_add_u32_e32 v66, 0x4b, v191
	s_nop 0
	v_cndmask_b32_e32 v88, v176, v88, vcc
	v_cmp_lt_u32_e32 vcc, s29, v66
	v_add_u32_e32 v66, 0x6b, v191
	s_nop 0
	v_cndmask_b32_e32 v105, v176, v73, vcc
	v_cmp_lt_u32_e32 vcc, s29, v66
	v_add_u32_e32 v66, 0x50, v191
	s_nop 0
	v_cndmask_b32_e32 v89, v176, v89, vcc
	v_cmp_lt_u32_e32 vcc, s29, v66
	v_add_u32_e32 v66, 0x70, v191
	s_nop 0
	v_cndmask_b32_e32 v106, v176, v74, vcc
	v_cmp_lt_u32_e32 vcc, s29, v66
	v_add_u32_e32 v66, 0x51, v191
	s_nop 0
	v_cndmask_b32_e32 v90, v176, v90, vcc
	v_cmp_lt_u32_e32 vcc, s29, v66
	v_add_u32_e32 v66, 0x71, v191
	s_nop 0
	v_cndmask_b32_e32 v107, v176, v75, vcc
	v_cmp_lt_u32_e32 vcc, s29, v66
	v_add_u32_e32 v66, 0x52, v191
	s_nop 0
	v_cndmask_b32_e32 v91, v176, v91, vcc
	v_cmp_lt_u32_e32 vcc, s29, v66
	v_add_u32_e32 v66, 0x72, v191
	s_nop 0
	v_cndmask_b32_e32 v76, v176, v76, vcc
	v_cmp_lt_u32_e32 vcc, s29, v66
	v_add_u32_e32 v66, 0x53, v191
	s_nop 0
	v_cndmask_b32_e32 v69, v176, v92, vcc
	v_cmp_lt_u32_e32 vcc, s29, v66
	v_add_u32_e32 v66, 0x73, v191
	s_nop 0
	v_cndmask_b32_e32 v77, v176, v77, vcc
	v_cmp_lt_u32_e32 vcc, s29, v66
	v_add_u32_e32 v66, 0x58, v191
	s_nop 0
	v_cndmask_b32_e32 v70, v176, v93, vcc
	v_cmp_lt_u32_e32 vcc, s29, v66
	v_add_u32_e32 v66, 0x78, v191
	s_nop 0
	v_cndmask_b32_e32 v75, v176, v78, vcc
	v_cmp_lt_u32_e32 vcc, s29, v66
	v_add_u32_e32 v66, 0x59, v191
	s_nop 0
	v_cndmask_b32_e32 v71, v176, v94, vcc
	v_cmp_lt_u32_e32 vcc, s29, v66
	v_add_u32_e32 v66, 0x79, v191
	s_nop 0
	v_cndmask_b32_e32 v72, v176, v79, vcc
	v_cmp_lt_u32_e32 vcc, s29, v66
	s_nop 1
	v_cndmask_b32_e32 v66, v176, v95, vcc
	v_cmp_lt_u32_e32 vcc, s29, v67
	v_add_u32_e32 v67, 0x7a, v191
	s_nop 0
	v_cndmask_b32_e32 v73, v176, v80, vcc
	v_cmp_lt_u32_e32 vcc, s29, v67
	s_nop 1
	v_cndmask_b32_e32 v67, v176, v96, vcc
	v_cmp_lt_u32_e32 vcc, s29, v68
	v_add_u32_e32 v68, 0x7b, v191
	s_nop 0
	v_cndmask_b32_e32 v74, v176, v81, vcc
	v_cmp_lt_u32_e32 vcc, s29, v68
	s_nop 1
	v_cndmask_b32_e32 v68, v176, v97, vcc

.LBB0_1494:
	s_andn2_b64 vcc, exec, s[34:35]
	s_cbranch_vccnz .LBB0_1501
	s_and_b32 s6, s12, 1
	s_lshl_b32 s7, s6, 12
	v_add_u32_e32 v1, s7, v230
	v_lshl_add_u32 v2, s6, 10, v229
	s_waitcnt lgkmcnt(0)
	ds_read2st64_b32 v[182:183], v1 offset0:4 offset1:5
	ds_read2st64_b32 v[180:181], v1 offset0:6 offset1:7
	ds_read_b128 v[128:131], v2
	ds_read_b128 v[112:115], v2 offset:16
	ds_read_b128 v[124:127], v2 offset:512
	ds_read_b128 v[108:111], v2 offset:528
	s_and_b64 vcc, exec, s[58:59]
	v_lshlrev_b32_e32 v2, 1, v206
	s_mov_b32 s98, 0x3fb8aa3b
	s_mov_b32 s99, 0x3fb8aa3b
	s_mov_b32 s100, 0x3f317218
	s_mov_b32 s101, 0x3f317218
	s_waitcnt lgkmcnt(0)
	v_pk_mul_f32 v[128:129], v[128:129], s[98:99]
	v_pk_mul_f32 v[130:131], v[130:131], s[98:99]
	v_pk_mul_f32 v[112:113], v[112:113], s[98:99]
	v_pk_mul_f32 v[114:115], v[114:115], s[98:99]
	v_pk_mul_f32 v[124:125], v[124:125], s[100:101]
	v_pk_mul_f32 v[126:127], v[126:127], s[100:101]
	v_pk_mul_f32 v[108:109], v[108:109], s[100:101]
	v_pk_mul_f32 v[110:111], v[110:111], s[100:101]
	s_cbranch_vccz .LBB0_1497
	ds_read2st64_b32 v[184:185], v1 offset1:1
	v_cvt_f32_i32_e32 v187, v177
	v_cvt_f32_i32_e32 v186, v176
	ds_read2st64_b32 v[176:177], v1 offset0:2 offset1:3
	v_cvt_f32_i32_e32 v179, v179
	s_waitcnt lgkmcnt(0)
	v_pk_mul_f32 v[188:189], v[128:129], v[184:185] op_sel_hi:[1,0]
	v_cvt_f32_i32_e32 v178, v178
	v_pk_mul_f32 v[186:187], v[188:189], v[186:187]
	v_pk_mul_f32 v[192:193], v[130:131], v[184:185] op_sel_hi:[1,0]
	v_exp_f32_e64 v1, -v186
	v_exp_f32_e64 v3, -v187
	v_pk_mul_f32 v[178:179], v[192:193], v[178:179]
	v_add_f32_e32 v1, 1.0, v1
	v_rcp_f32_e32 v188, v1
	v_add_f32_e32 v1, 1.0, v3
	v_rcp_f32_e32 v189, v1
	v_cvt_f32_i32_e32 v173, v173
	v_cvt_f32_i32_e32 v172, v172
	v_exp_f32_e64 v1, -v178
	v_pk_mul_f32 v[190:191], v[124:125], v[184:185] op_sel_hi:[1,0]
	v_pk_mul_f32 v[186:187], v[186:187], v[188:189]
	v_pk_mul_f32 v[172:173], v[190:191], v[172:173]
	v_add_f32_e32 v1, 1.0, v1
	v_pk_mul_f32 v[172:173], v[172:173], v[186:187]
	v_rcp_f32_e32 v186, v1
	v_exp_f32_e64 v1, -v179
	v_cvt_f32_i32_e32 v169, v169
	v_cvt_f32_i32_e32 v168, v168
	v_pk_mul_f32 v[190:191], v[112:113], v[184:185] op_sel_hi:[1,0]
	v_add_f32_e32 v1, 1.0, v1
	v_rcp_f32_e32 v187, v1
	v_pk_mul_f32 v[168:169], v[190:191], v[168:169]
	v_cvt_f32_i32_e32 v175, v175
	v_cvt_f32_i32_e32 v174, v174
	v_exp_f32_e64 v1, -v168
	v_pk_mul_f32 v[188:189], v[126:127], v[184:185] op_sel_hi:[1,0]
	v_pk_mul_f32 v[178:179], v[178:179], v[186:187]
	v_pk_mul_f32 v[174:175], v[188:189], v[174:175]
	v_add_f32_e32 v1, 1.0, v1
	v_pk_mul_f32 v[174:175], v[174:175], v[178:179]
	v_rcp_f32_e32 v178, v1
	v_exp_f32_e64 v1, -v169
	v_cvt_f32_i32_e32 v171, v171
	v_cvt_f32_i32_e32 v170, v170
	v_pk_mul_f32 v[186:187], v[114:115], v[184:185] op_sel_hi:[1,0]
	v_add_f32_e32 v1, 1.0, v1
	v_rcp_f32_e32 v179, v1
	v_pk_mul_f32 v[170:171], v[186:187], v[170:171]
	v_cvt_f32_i32_e32 v165, v165
	v_exp_f32_e64 v1, -v170
	v_exp_f32_e64 v3, -v171
	v_cvt_f32_i32_e32 v164, v164
	v_add_f32_e32 v1, 1.0, v1
	v_pk_mul_f32 v[168:169], v[168:169], v[178:179]
	v_rcp_f32_e32 v178, v1
	v_add_f32_e32 v1, 1.0, v3
	v_cvt_f32_i32_e32 v167, v167
	v_cvt_f32_i32_e32 v166, v166
	v_rcp_f32_e32 v179, v1
	v_pk_mul_f32 v[186:187], v[108:109], v[184:185] op_sel_hi:[1,0]
	v_cvt_f32_i32_e32 v161, v161
	v_pk_mul_f32 v[164:165], v[186:187], v[164:165]
	v_cvt_f32_i32_e32 v160, v160
	v_pk_mul_f32 v[164:165], v[164:165], v[168:169]
	v_pk_mul_f32 v[168:169], v[110:111], v[184:185] op_sel_hi:[1,0]
	s_lshl_b32 s41, s56, 8
	v_pk_mul_f32 v[166:167], v[168:169], v[166:167]
	v_pk_mul_f32 v[168:169], v[170:171], v[178:179]
	v_add_u32_e32 v1, s41, v221
	v_pk_mul_f32 v[170:171], v[166:167], v[168:169]
	v_cvt_pk_bf16_f32 v166, v172, v173
	v_mov_b32_e32 v172, v185
	v_cvt_pk_bf16_f32 v167, v174, v175
	v_cvt_pk_bf16_f32 v168, v164, v165
	v_mov_b64_e32 v[164:165], s[30:31]
	v_pk_mul_f32 v[174:175], v[128:129], v[172:173] op_sel_hi:[1,0]
	v_cvt_pk_bf16_f32 v169, v170, v171
	v_mad_i64_i32 v[170:171], s[6:7], v1, s66, v[164:165]
	v_pk_mul_f32 v[160:161], v[174:175], v[160:161]
	s_lshl_b32 s6, s54, 7
	s_ashr_i32 s7, s6, 31
	v_exp_f32_e64 v1, -v160
	s_lshl_b64 s[8:9], s[6:7], 1
	v_lshl_add_u64 v[170:171], v[170:171], 0, s[8:9]
	s_lshl_b32 s12, s79, 1
	v_lshl_add_u64 v[170:171], v[170:171], 0, s[12:13]
	v_mov_b32_e32 v3, v0
	v_lshl_add_u64 v[170:171], v[170:171], 0, v[2:3]
	v_add_f32_e32 v1, 1.0, v1
	global_store_dwordx4 v[170:171], v[166:169], off
	v_cvt_f32_i32_e32 v163, v163
	v_cvt_f32_i32_e32 v162, v162
	v_rcp_f32_e32 v166, v1
	v_exp_f32_e64 v1, -v161
	v_pk_mul_f32 v[170:171], v[130:131], v[172:173] op_sel_hi:[1,0]
	v_cvt_f32_i32_e32 v157, v157
	v_pk_mul_f32 v[162:163], v[170:171], v[162:163]
	v_add_f32_e32 v1, 1.0, v1
	v_rcp_f32_e32 v167, v1
	v_cvt_f32_i32_e32 v156, v156
	v_exp_f32_e64 v1, -v162
	v_pk_mul_f32 v[168:169], v[124:125], v[172:173] op_sel_hi:[1,0]
	v_pk_mul_f32 v[160:161], v[160:161], v[166:167]
	v_pk_mul_f32 v[156:157], v[168:169], v[156:157]
	v_add_f32_e32 v1, 1.0, v1
	v_pk_mul_f32 v[156:157], v[156:157], v[160:161]
	v_rcp_f32_e32 v160, v1
	v_exp_f32_e64 v1, -v163
	v_cvt_f32_i32_e32 v153, v153
	v_cvt_f32_i32_e32 v152, v152
	v_pk_mul_f32 v[168:169], v[112:113], v[172:173] op_sel_hi:[1,0]
	v_add_f32_e32 v1, 1.0, v1
	v_rcp_f32_e32 v161, v1
	v_pk_mul_f32 v[152:153], v[168:169], v[152:153]
	v_cvt_f32_i32_e32 v159, v159
	v_cvt_f32_i32_e32 v158, v158
	v_exp_f32_e64 v1, -v152
	v_pk_mul_f32 v[166:167], v[126:127], v[172:173] op_sel_hi:[1,0]
	v_pk_mul_f32 v[160:161], v[162:163], v[160:161]
	v_pk_mul_f32 v[158:159], v[166:167], v[158:159]
	v_add_f32_e32 v1, 1.0, v1
	v_pk_mul_f32 v[158:159], v[158:159], v[160:161]
	v_rcp_f32_e32 v160, v1
	v_exp_f32_e64 v1, -v153
	v_cvt_f32_i32_e32 v155, v155
	v_cvt_f32_i32_e32 v154, v154
	v_pk_mul_f32 v[162:163], v[114:115], v[172:173] op_sel_hi:[1,0]
	v_add_f32_e32 v1, 1.0, v1
	v_rcp_f32_e32 v161, v1
	v_pk_mul_f32 v[154:155], v[162:163], v[154:155]
	v_cvt_f32_i32_e32 v149, v149
	v_exp_f32_e64 v1, -v154
	v_pk_mul_f32 v[152:153], v[152:153], v[160:161]
	v_exp_f32_e64 v161, -v155
	v_cvt_f32_i32_e32 v148, v148
	v_add_f32_e32 v1, 1.0, v1
	v_rcp_f32_e32 v160, v1
	v_add_f32_e32 v1, 1.0, v161
	v_cvt_f32_i32_e32 v151, v151
	v_cvt_f32_i32_e32 v150, v150
	v_rcp_f32_e32 v161, v1
	v_pk_mul_f32 v[162:163], v[108:109], v[172:173] op_sel_hi:[1,0]
	v_cvt_f32_i32_e32 v145, v145
	v_pk_mul_f32 v[148:149], v[162:163], v[148:149]
	v_cvt_f32_i32_e32 v144, v144
	v_pk_mul_f32 v[152:153], v[148:149], v[152:153]
	v_pk_mul_f32 v[148:149], v[110:111], v[172:173] op_sel_hi:[1,0]
	v_add_u32_e32 v1, s41, v222
	v_pk_mul_f32 v[148:149], v[148:149], v[150:151]
	v_pk_mul_f32 v[150:151], v[154:155], v[160:161]
	v_cvt_f32_i32_e32 v147, v147
	v_pk_mul_f32 v[154:155], v[148:149], v[150:151]
	v_cvt_pk_bf16_f32 v150, v152, v153
	v_cvt_pk_bf16_f32 v151, v154, v155
	v_pk_mul_f32 v[154:155], v[128:129], v[176:177] op_sel_hi:[1,0]
	v_mad_i64_i32 v[152:153], s[58:59], v1, s66, v[164:165]
	v_pk_mul_f32 v[144:145], v[154:155], v[144:145]
	v_lshl_add_u64 v[152:153], v[152:153], 0, s[8:9]
	v_exp_f32_e64 v1, -v144
	v_lshl_add_u64 v[152:153], v[152:153], 0, s[12:13]
	v_cvt_pk_bf16_f32 v148, v156, v157
	v_cvt_pk_bf16_f32 v149, v158, v159
	v_lshl_add_u64 v[152:153], v[152:153], 0, v[2:3]
	v_add_f32_e32 v1, 1.0, v1
	global_store_dwordx4 v[152:153], v[148:151], off
	v_cvt_f32_i32_e32 v146, v146
	v_pk_mul_f32 v[152:153], v[130:131], v[176:177] op_sel_hi:[1,0]
	v_rcp_f32_e32 v148, v1
	v_exp_f32_e64 v1, -v145
	v_pk_mul_f32 v[146:147], v[152:153], v[146:147]
	v_cvt_f32_i32_e32 v141, v141
	v_cvt_f32_i32_e32 v140, v140
	v_add_f32_e32 v1, 1.0, v1
	v_rcp_f32_e32 v149, v1
	v_exp_f32_e64 v1, -v146
	v_pk_mul_f32 v[150:151], v[124:125], v[176:177] op_sel_hi:[1,0]
	v_pk_mul_f32 v[144:145], v[144:145], v[148:149]
	v_pk_mul_f32 v[140:141], v[150:151], v[140:141]
	v_add_f32_e32 v1, 1.0, v1
	v_pk_mul_f32 v[140:141], v[140:141], v[144:145]
	v_rcp_f32_e32 v144, v1
	v_exp_f32_e64 v1, -v147
	v_cvt_f32_i32_e32 v137, v137
	v_cvt_f32_i32_e32 v136, v136
	v_pk_mul_f32 v[150:151], v[112:113], v[176:177] op_sel_hi:[1,0]
	v_add_f32_e32 v1, 1.0, v1
	v_rcp_f32_e32 v145, v1
	v_pk_mul_f32 v[136:137], v[150:151], v[136:137]
	v_cvt_f32_i32_e32 v143, v143
	v_cvt_f32_i32_e32 v142, v142
	v_exp_f32_e64 v1, -v136
	v_pk_mul_f32 v[148:149], v[126:127], v[176:177] op_sel_hi:[1,0]
	v_pk_mul_f32 v[144:145], v[146:147], v[144:145]
	v_pk_mul_f32 v[142:143], v[148:149], v[142:143]
	v_add_f32_e32 v1, 1.0, v1
	v_pk_mul_f32 v[142:143], v[142:143], v[144:145]
	v_rcp_f32_e32 v144, v1
	v_exp_f32_e64 v1, -v137
	v_cvt_f32_i32_e32 v139, v139
	v_cvt_f32_i32_e32 v138, v138
	v_pk_mul_f32 v[146:147], v[114:115], v[176:177] op_sel_hi:[1,0]
	v_add_f32_e32 v1, 1.0, v1
	v_rcp_f32_e32 v145, v1
	v_pk_mul_f32 v[138:139], v[146:147], v[138:139]
	v_cvt_f32_i32_e32 v133, v133
	v_exp_f32_e64 v1, -v138
	v_pk_mul_f32 v[136:137], v[136:137], v[144:145]
	v_exp_f32_e64 v145, -v139
	v_cvt_f32_i32_e32 v132, v132
	v_add_f32_e32 v1, 1.0, v1
	v_rcp_f32_e32 v144, v1
	v_add_f32_e32 v1, 1.0, v145
	v_cvt_f32_i32_e32 v135, v135
	v_cvt_f32_i32_e32 v134, v134
	v_rcp_f32_e32 v145, v1
	v_pk_mul_f32 v[146:147], v[108:109], v[176:177] op_sel_hi:[1,0]
	v_cvt_f32_i32_e32 v121, v121
	v_pk_mul_f32 v[132:133], v[146:147], v[132:133]
	v_cvt_f32_i32_e32 v120, v120
	v_pk_mul_f32 v[136:137], v[132:133], v[136:137]
	v_pk_mul_f32 v[132:133], v[110:111], v[176:177] op_sel_hi:[1,0]
	v_add_u32_e32 v1, s41, v223
	v_pk_mul_f32 v[132:133], v[132:133], v[134:135]
	v_pk_mul_f32 v[134:135], v[138:139], v[144:145]
	v_cvt_f32_i32_e32 v123, v123
	v_pk_mul_f32 v[138:139], v[132:133], v[134:135]
	v_cvt_pk_bf16_f32 v132, v140, v141
	v_cvt_pk_bf16_f32 v135, v138, v139
	v_mov_b32_e32 v138, v177
	v_pk_mul_f32 v[140:141], v[128:129], v[138:139] op_sel_hi:[1,0]
	v_cvt_pk_bf16_f32 v134, v136, v137
	v_pk_mul_f32 v[120:121], v[140:141], v[120:121]
	v_mad_i64_i32 v[136:137], s[58:59], v1, s66, v[164:165]
	v_exp_f32_e64 v1, -v120
	v_lshl_add_u64 v[136:137], v[136:137], 0, s[8:9]
	v_lshl_add_u64 v[136:137], v[136:137], 0, s[12:13]
	v_cvt_pk_bf16_f32 v133, v142, v143
	v_lshl_add_u64 v[136:137], v[136:137], 0, v[2:3]
	v_add_f32_e32 v1, 1.0, v1
	global_store_dwordx4 v[136:137], v[132:135], off
	v_cvt_f32_i32_e32 v122, v122
	v_pk_mul_f32 v[136:137], v[130:131], v[138:139] op_sel_hi:[1,0]
	v_rcp_f32_e32 v132, v1
	v_exp_f32_e64 v1, -v121
	v_pk_mul_f32 v[122:123], v[136:137], v[122:123]
	v_cvt_f32_i32_e32 v117, v117
	v_cvt_f32_i32_e32 v116, v116
	v_add_f32_e32 v1, 1.0, v1
	v_rcp_f32_e32 v133, v1
	v_exp_f32_e64 v1, -v122
	v_pk_mul_f32 v[134:135], v[124:125], v[138:139] op_sel_hi:[1,0]
	v_pk_mul_f32 v[120:121], v[120:121], v[132:133]
	v_pk_mul_f32 v[116:117], v[134:135], v[116:117]
	v_add_f32_e32 v1, 1.0, v1
	v_pk_mul_f32 v[116:117], v[116:117], v[120:121]
	v_rcp_f32_e32 v120, v1
	v_exp_f32_e64 v1, -v123
	v_cvt_f32_i32_e32 v105, v105
	v_cvt_f32_i32_e32 v104, v104
	v_pk_mul_f32 v[134:135], v[112:113], v[138:139] op_sel_hi:[1,0]
	v_add_f32_e32 v1, 1.0, v1
	v_rcp_f32_e32 v121, v1
	v_pk_mul_f32 v[104:105], v[134:135], v[104:105]
	v_cvt_f32_i32_e32 v119, v119
	v_cvt_f32_i32_e32 v118, v118
	v_exp_f32_e64 v1, -v104
	v_pk_mul_f32 v[132:133], v[126:127], v[138:139] op_sel_hi:[1,0]
	v_pk_mul_f32 v[120:121], v[122:123], v[120:121]
	v_pk_mul_f32 v[118:119], v[132:133], v[118:119]
	v_add_f32_e32 v1, 1.0, v1
	v_pk_mul_f32 v[118:119], v[118:119], v[120:121]
	v_rcp_f32_e32 v120, v1
	v_exp_f32_e64 v1, -v105
	v_cvt_f32_i32_e32 v107, v107
	v_cvt_f32_i32_e32 v106, v106
	v_pk_mul_f32 v[122:123], v[114:115], v[138:139] op_sel_hi:[1,0]
	v_add_f32_e32 v1, 1.0, v1
	v_rcp_f32_e32 v121, v1
	v_pk_mul_f32 v[106:107], v[122:123], v[106:107]
	v_cvt_f32_i32_e32 v101, v101
	v_exp_f32_e64 v1, -v106
	v_pk_mul_f32 v[104:105], v[104:105], v[120:121]
	v_exp_f32_e64 v121, -v107
	v_cvt_f32_i32_e32 v100, v100
	v_add_f32_e32 v1, 1.0, v1
	v_rcp_f32_e32 v120, v1
	v_add_f32_e32 v1, 1.0, v121
	v_cvt_f32_i32_e32 v103, v103
	v_cvt_f32_i32_e32 v102, v102
	v_rcp_f32_e32 v121, v1
	v_pk_mul_f32 v[122:123], v[108:109], v[138:139] op_sel_hi:[1,0]
	v_add_u32_e32 v1, s41, v224
	v_pk_mul_f32 v[100:101], v[122:123], v[100:101]
	s_nop 0
	v_pk_mul_f32 v[104:105], v[100:101], v[104:105]
	v_pk_mul_f32 v[100:101], v[110:111], v[138:139] op_sel_hi:[1,0]
	s_nop 0
	v_pk_mul_f32 v[100:101], v[100:101], v[102:103]
	v_pk_mul_f32 v[102:103], v[106:107], v[120:121]
	s_nop 0
	v_pk_mul_f32 v[106:107], v[100:101], v[102:103]
	v_cvt_pk_bf16_f32 v102, v104, v105
	v_mad_i64_i32 v[104:105], s[58:59], v1, s66, v[164:165]
	v_lshl_add_u64 v[104:105], v[104:105], 0, s[8:9]
	v_lshl_add_u64 v[104:105], v[104:105], 0, s[12:13]
	v_cvt_pk_bf16_f32 v100, v116, v117
	v_cvt_pk_bf16_f32 v101, v118, v119
	v_cvt_pk_bf16_f32 v103, v106, v107
	v_lshl_add_u64 v[104:105], v[104:105], 0, v[2:3]
	global_store_dwordx4 v[104:105], v[100:103], off
	s_cbranch_execz .LBB0_1498
	s_branch .LBB0_1499

.LBB0_1499:
	s_andn2_b64 vcc, exec, s[48:49]
	s_cbranch_vccnz .LBB0_1501
	v_cvt_f32_i32_e32 v97, v97
	v_cvt_f32_i32_e32 v96, v96
	s_waitcnt lgkmcnt(0)
	v_pk_mul_f32 v[100:101], v[182:183], v[128:129] op_sel_hi:[0,1]
	v_cvt_f32_i32_e32 v93, v93
	v_cvt_f32_i32_e32 v92, v92
	v_pk_mul_f32 v[96:97], v[100:101], v[96:97]
	v_cvt_f32_i32_e32 v99, v99
	v_exp_f32_e64 v1, -v96
	v_cvt_f32_i32_e32 v98, v98
	v_pk_mul_f32 v[102:103], v[182:183], v[124:125] op_sel_hi:[0,1]
	v_add_f32_e32 v1, 1.0, v1
	v_rcp_f32_e32 v100, v1
	v_exp_f32_e64 v1, -v97
	v_pk_mul_f32 v[92:93], v[102:103], v[92:93]
	v_pk_mul_f32 v[102:103], v[182:183], v[130:131] op_sel_hi:[0,1]
	v_pk_mul_f32 v[98:99], v[102:103], v[98:99]
	v_add_f32_e32 v1, 1.0, v1
	v_rcp_f32_e32 v101, v1
	v_exp_f32_e64 v1, -v98
	v_cvt_f32_i32_e32 v89, v89
	v_pk_mul_f32 v[96:97], v[96:97], v[100:101]
	v_cvt_f32_i32_e32 v88, v88
	v_add_f32_e32 v1, 1.0, v1
	v_rcp_f32_e32 v100, v1
	v_exp_f32_e64 v1, -v99
	v_pk_mul_f32 v[102:103], v[182:183], v[112:113] op_sel_hi:[0,1]
	v_pk_mul_f32 v[88:89], v[102:103], v[88:89]
	v_cvt_f32_i32_e32 v95, v95
	v_add_f32_e32 v1, 1.0, v1
	v_rcp_f32_e32 v101, v1
	v_cvt_f32_i32_e32 v94, v94
	v_exp_f32_e64 v1, -v88
	v_pk_mul_f32 v[92:93], v[92:93], v[96:97]
	v_pk_mul_f32 v[96:97], v[182:183], v[126:127] op_sel_hi:[0,1]
	v_pk_mul_f32 v[94:95], v[96:97], v[94:95]
	v_pk_mul_f32 v[96:97], v[98:99], v[100:101]
	v_add_f32_e32 v1, 1.0, v1
	v_pk_mul_f32 v[94:95], v[94:95], v[96:97]
	v_rcp_f32_e32 v96, v1
	v_exp_f32_e64 v1, -v89
	v_cvt_f32_i32_e32 v91, v91
	v_cvt_f32_i32_e32 v90, v90
	v_pk_mul_f32 v[98:99], v[182:183], v[114:115] op_sel_hi:[0,1]
	v_add_f32_e32 v1, 1.0, v1
	v_rcp_f32_e32 v97, v1
	v_pk_mul_f32 v[90:91], v[98:99], v[90:91]
	v_cvt_f32_i32_e32 v85, v85
	v_exp_f32_e64 v1, -v90
	v_exp_f32_e64 v3, -v91
	v_cvt_f32_i32_e32 v84, v84
	v_add_f32_e32 v1, 1.0, v1
	v_pk_mul_f32 v[88:89], v[88:89], v[96:97]
	v_rcp_f32_e32 v96, v1
	v_add_f32_e32 v1, 1.0, v3
	v_cvt_f32_i32_e32 v87, v87
	v_cvt_f32_i32_e32 v86, v86
	v_rcp_f32_e32 v97, v1
	v_pk_mul_f32 v[98:99], v[182:183], v[108:109] op_sel_hi:[0,1]
	v_pk_mul_f32 v[84:85], v[98:99], v[84:85]
	v_cvt_f32_i32_e32 v81, v81
	v_pk_mul_f32 v[84:85], v[84:85], v[88:89]
	v_pk_mul_f32 v[88:89], v[182:183], v[110:111] op_sel_hi:[0,1]
	v_cvt_f32_i32_e32 v80, v80
	v_pk_mul_f32 v[86:87], v[88:89], v[86:87]
	v_pk_mul_f32 v[88:89], v[90:91], v[96:97]
	v_add_u32_e32 v1, s41, v225
	v_pk_mul_f32 v[90:91], v[86:87], v[88:89]
	v_cvt_pk_bf16_f32 v86, v92, v93
	v_mov_b32_e32 v92, v183
	v_cvt_pk_bf16_f32 v87, v94, v95
	v_pk_mul_f32 v[94:95], v[92:93], v[128:129] op_sel_hi:[0,1]
	v_cvt_pk_bf16_f32 v88, v84, v85
	v_mov_b64_e32 v[84:85], s[30:31]
	v_pk_mul_f32 v[80:81], v[94:95], v[80:81]
	v_cvt_pk_bf16_f32 v89, v90, v91
	v_mad_i64_i32 v[90:91], s[8:9], v1, s66, v[84:85]
	v_exp_f32_e64 v1, -v80
	s_lshl_b64 s[6:7], s[6:7], 1
	v_lshl_add_u64 v[90:91], v[90:91], 0, s[6:7]
	s_lshl_b32 s12, s79, 1
	v_lshl_add_u64 v[90:91], v[90:91], 0, s[12:13]
	v_mov_b32_e32 v3, v0
	v_lshl_add_u64 v[90:91], v[90:91], 0, v[2:3]
	v_add_f32_e32 v1, 1.0, v1
	global_store_dwordx4 v[90:91], v[86:89], off
	v_cvt_f32_i32_e32 v83, v83
	v_cvt_f32_i32_e32 v82, v82
	v_rcp_f32_e32 v86, v1
	v_exp_f32_e64 v1, -v81
	v_pk_mul_f32 v[90:91], v[92:93], v[130:131] op_sel_hi:[0,1]
	v_pk_mul_f32 v[82:83], v[90:91], v[82:83]
	v_cvt_f32_i32_e32 v77, v77
	v_add_f32_e32 v1, 1.0, v1
	v_rcp_f32_e32 v87, v1
	v_cvt_f32_i32_e32 v76, v76
	v_exp_f32_e64 v1, -v82
	v_pk_mul_f32 v[88:89], v[92:93], v[124:125] op_sel_hi:[0,1]
	v_pk_mul_f32 v[80:81], v[80:81], v[86:87]
	v_pk_mul_f32 v[76:77], v[88:89], v[76:77]
	v_add_f32_e32 v1, 1.0, v1
	v_pk_mul_f32 v[76:77], v[76:77], v[80:81]
	v_rcp_f32_e32 v80, v1
	v_exp_f32_e64 v1, -v83
	v_cvt_f32_i32_e32 v73, v73
	v_cvt_f32_i32_e32 v72, v72
	v_pk_mul_f32 v[88:89], v[92:93], v[112:113] op_sel_hi:[0,1]
	v_add_f32_e32 v1, 1.0, v1
	v_rcp_f32_e32 v81, v1
	v_pk_mul_f32 v[72:73], v[88:89], v[72:73]
	v_cvt_f32_i32_e32 v79, v79
	v_cvt_f32_i32_e32 v78, v78
	v_exp_f32_e64 v1, -v72
	v_pk_mul_f32 v[86:87], v[92:93], v[126:127] op_sel_hi:[0,1]
	v_pk_mul_f32 v[80:81], v[82:83], v[80:81]
	v_pk_mul_f32 v[78:79], v[86:87], v[78:79]
	v_add_f32_e32 v1, 1.0, v1
	v_pk_mul_f32 v[78:79], v[78:79], v[80:81]
	v_rcp_f32_e32 v80, v1
	v_exp_f32_e64 v1, -v73
	v_cvt_f32_i32_e32 v75, v75
	v_cvt_f32_i32_e32 v74, v74
	v_pk_mul_f32 v[82:83], v[92:93], v[114:115] op_sel_hi:[0,1]
	v_add_f32_e32 v1, 1.0, v1
	v_rcp_f32_e32 v81, v1
	v_pk_mul_f32 v[74:75], v[82:83], v[74:75]
	v_cvt_f32_i32_e32 v69, v69
	v_exp_f32_e64 v1, -v74
	v_pk_mul_f32 v[72:73], v[72:73], v[80:81]
	v_exp_f32_e64 v81, -v75
	v_cvt_f32_i32_e32 v68, v68
	v_add_f32_e32 v1, 1.0, v1
	v_rcp_f32_e32 v80, v1
	v_add_f32_e32 v1, 1.0, v81
	v_cvt_f32_i32_e32 v71, v71
	v_cvt_f32_i32_e32 v70, v70
	v_rcp_f32_e32 v81, v1
	v_pk_mul_f32 v[82:83], v[92:93], v[108:109] op_sel_hi:[0,1]
	v_pk_mul_f32 v[68:69], v[82:83], v[68:69]
	v_cvt_f32_i32_e32 v65, v65
	v_pk_mul_f32 v[72:73], v[68:69], v[72:73]
	v_pk_mul_f32 v[68:69], v[92:93], v[110:111] op_sel_hi:[0,1]
	v_cvt_f32_i32_e32 v64, v64
	v_pk_mul_f32 v[68:69], v[68:69], v[70:71]
	v_pk_mul_f32 v[70:71], v[74:75], v[80:81]
	v_add_u32_e32 v1, s41, v226
	v_pk_mul_f32 v[74:75], v[68:69], v[70:71]
	v_cvt_pk_bf16_f32 v70, v72, v73
	v_cvt_pk_bf16_f32 v71, v74, v75
	v_pk_mul_f32 v[74:75], v[180:181], v[128:129] op_sel_hi:[0,1]
	v_pk_mul_f32 v[64:65], v[74:75], v[64:65]
	v_mad_i64_i32 v[72:73], s[8:9], v1, s66, v[84:85]
	v_exp_f32_e64 v1, -v64
	v_lshl_add_u64 v[72:73], v[72:73], 0, s[6:7]
	v_lshl_add_u64 v[72:73], v[72:73], 0, s[12:13]
	v_cvt_pk_bf16_f32 v68, v76, v77
	v_cvt_pk_bf16_f32 v69, v78, v79
	v_lshl_add_u64 v[72:73], v[72:73], 0, v[2:3]
	v_add_f32_e32 v1, 1.0, v1
	global_store_dwordx4 v[72:73], v[68:71], off
	v_cvt_f32_i32_e32 v67, v67
	v_cvt_f32_i32_e32 v66, v66
	v_rcp_f32_e32 v68, v1
	v_exp_f32_e64 v1, -v65
	v_pk_mul_f32 v[72:73], v[180:181], v[130:131] op_sel_hi:[0,1]
	v_pk_mul_f32 v[66:67], v[72:73], v[66:67]
	v_cvt_f32_i32_e32 v61, v61
	v_add_f32_e32 v1, 1.0, v1
	v_rcp_f32_e32 v69, v1
	v_cvt_f32_i32_e32 v60, v60
	v_exp_f32_e64 v1, -v66
	v_pk_mul_f32 v[70:71], v[180:181], v[124:125] op_sel_hi:[0,1]
	v_pk_mul_f32 v[64:65], v[64:65], v[68:69]
	v_pk_mul_f32 v[60:61], v[70:71], v[60:61]
	v_add_f32_e32 v1, 1.0, v1
	v_pk_mul_f32 v[60:61], v[60:61], v[64:65]
	v_rcp_f32_e32 v64, v1
	v_exp_f32_e64 v1, -v67
	v_cvt_f32_i32_e32 v57, v57
	v_cvt_f32_i32_e32 v56, v56
	v_pk_mul_f32 v[70:71], v[180:181], v[112:113] op_sel_hi:[0,1]
	v_add_f32_e32 v1, 1.0, v1
	v_rcp_f32_e32 v65, v1
	v_pk_mul_f32 v[56:57], v[70:71], v[56:57]
	v_cvt_f32_i32_e32 v63, v63
	v_cvt_f32_i32_e32 v62, v62
	v_exp_f32_e64 v1, -v56
	v_pk_mul_f32 v[68:69], v[180:181], v[126:127] op_sel_hi:[0,1]
	v_pk_mul_f32 v[64:65], v[66:67], v[64:65]
	v_pk_mul_f32 v[62:63], v[68:69], v[62:63]
	v_add_f32_e32 v1, 1.0, v1
	v_pk_mul_f32 v[62:63], v[62:63], v[64:65]
	v_rcp_f32_e32 v64, v1
	v_exp_f32_e64 v1, -v57
	v_cvt_f32_i32_e32 v59, v59
	v_cvt_f32_i32_e32 v58, v58
	v_pk_mul_f32 v[66:67], v[180:181], v[114:115] op_sel_hi:[0,1]
	v_add_f32_e32 v1, 1.0, v1
	v_rcp_f32_e32 v65, v1
	v_pk_mul_f32 v[58:59], v[66:67], v[58:59]
	v_cvt_f32_i32_e32 v53, v53
	v_exp_f32_e64 v1, -v58
	v_pk_mul_f32 v[56:57], v[56:57], v[64:65]
	v_exp_f32_e64 v65, -v59
	v_cvt_f32_i32_e32 v52, v52
	v_add_f32_e32 v1, 1.0, v1
	v_rcp_f32_e32 v64, v1
	v_add_f32_e32 v1, 1.0, v65
	v_cvt_f32_i32_e32 v55, v55
	v_cvt_f32_i32_e32 v54, v54
	v_rcp_f32_e32 v65, v1
	v_pk_mul_f32 v[66:67], v[180:181], v[108:109] op_sel_hi:[0,1]
	v_pk_mul_f32 v[52:53], v[66:67], v[52:53]
	v_cvt_f32_i32_e32 v49, v49
	v_pk_mul_f32 v[56:57], v[52:53], v[56:57]
	v_pk_mul_f32 v[52:53], v[180:181], v[110:111] op_sel_hi:[0,1]
	v_pk_mul_f32 v[52:53], v[52:53], v[54:55]
	v_pk_mul_f32 v[54:55], v[58:59], v[64:65]
	v_cvt_f32_i32_e32 v48, v48
	v_pk_mul_f32 v[58:59], v[52:53], v[54:55]
	v_cvt_pk_bf16_f32 v52, v60, v61
	v_cvt_pk_bf16_f32 v55, v58, v59
	v_mov_b32_e32 v58, v181
	v_pk_mul_f32 v[60:61], v[58:59], v[128:129] op_sel_hi:[0,1]
	v_add_u32_e32 v1, s41, v227
	v_pk_mul_f32 v[48:49], v[60:61], v[48:49]
	v_cvt_pk_bf16_f32 v54, v56, v57
	v_mad_i64_i32 v[56:57], s[8:9], v1, s66, v[84:85]
	v_exp_f32_e64 v1, -v48
	v_lshl_add_u64 v[56:57], v[56:57], 0, s[6:7]
	v_lshl_add_u64 v[56:57], v[56:57], 0, s[12:13]
	v_cvt_pk_bf16_f32 v53, v62, v63
	v_lshl_add_u64 v[56:57], v[56:57], 0, v[2:3]
	v_add_f32_e32 v1, 1.0, v1
	global_store_dwordx4 v[56:57], v[52:55], off
	v_cvt_f32_i32_e32 v51, v51
	v_cvt_f32_i32_e32 v50, v50
	v_rcp_f32_e32 v52, v1
	v_exp_f32_e64 v1, -v49
	v_pk_mul_f32 v[56:57], v[58:59], v[130:131] op_sel_hi:[0,1]
	v_pk_mul_f32 v[50:51], v[56:57], v[50:51]
	v_cvt_f32_i32_e32 v45, v45
	v_add_f32_e32 v1, 1.0, v1
	v_rcp_f32_e32 v53, v1
	v_cvt_f32_i32_e32 v44, v44
	v_exp_f32_e64 v1, -v50
	v_pk_mul_f32 v[54:55], v[58:59], v[124:125] op_sel_hi:[0,1]
	v_pk_mul_f32 v[48:49], v[48:49], v[52:53]
	v_pk_mul_f32 v[44:45], v[54:55], v[44:45]
	v_add_f32_e32 v1, 1.0, v1
	v_pk_mul_f32 v[44:45], v[44:45], v[48:49]
	v_rcp_f32_e32 v48, v1
	v_exp_f32_e64 v1, -v51
	v_cvt_f32_i32_e32 v41, v41
	v_cvt_f32_i32_e32 v40, v40
	v_pk_mul_f32 v[54:55], v[58:59], v[112:113] op_sel_hi:[0,1]
	v_add_f32_e32 v1, 1.0, v1
	v_rcp_f32_e32 v49, v1
	v_pk_mul_f32 v[40:41], v[54:55], v[40:41]
	v_cvt_f32_i32_e32 v47, v47
	v_cvt_f32_i32_e32 v46, v46
	v_exp_f32_e64 v1, -v40
	v_pk_mul_f32 v[52:53], v[58:59], v[126:127] op_sel_hi:[0,1]
	v_pk_mul_f32 v[48:49], v[50:51], v[48:49]
	v_pk_mul_f32 v[46:47], v[52:53], v[46:47]
	v_add_f32_e32 v1, 1.0, v1
	v_pk_mul_f32 v[46:47], v[46:47], v[48:49]
	v_rcp_f32_e32 v48, v1
	v_exp_f32_e64 v1, -v41
	v_cvt_f32_i32_e32 v43, v43
	v_cvt_f32_i32_e32 v42, v42
	v_pk_mul_f32 v[50:51], v[58:59], v[114:115] op_sel_hi:[0,1]
	v_add_f32_e32 v1, 1.0, v1
	v_rcp_f32_e32 v49, v1
	v_pk_mul_f32 v[42:43], v[50:51], v[42:43]
	v_cvt_f32_i32_e32 v37, v37
	v_exp_f32_e64 v1, -v42
	v_pk_mul_f32 v[40:41], v[40:41], v[48:49]
	v_exp_f32_e64 v49, -v43
	v_cvt_f32_i32_e32 v36, v36
	v_add_f32_e32 v1, 1.0, v1
	v_rcp_f32_e32 v48, v1
	v_add_f32_e32 v1, 1.0, v49
	v_cvt_f32_i32_e32 v39, v39
	v_cvt_f32_i32_e32 v38, v38
	v_rcp_f32_e32 v49, v1
	v_pk_mul_f32 v[50:51], v[58:59], v[108:109] op_sel_hi:[0,1]
	v_pk_mul_f32 v[36:37], v[50:51], v[36:37]
	v_add_u32_e32 v1, s41, v228
	v_pk_mul_f32 v[40:41], v[36:37], v[40:41]
	v_pk_mul_f32 v[36:37], v[58:59], v[110:111] op_sel_hi:[0,1]
	v_pk_mul_f32 v[36:37], v[36:37], v[38:39]
	v_pk_mul_f32 v[38:39], v[42:43], v[48:49]
	s_nop 0
	v_pk_mul_f32 v[42:43], v[36:37], v[38:39]
	v_cvt_pk_bf16_f32 v38, v40, v41
	v_mad_i64_i32 v[40:41], s[8:9], v1, s66, v[84:85]
	v_lshl_add_u64 v[40:41], v[40:41], 0, s[6:7]
	v_lshl_add_u64 v[40:41], v[40:41], 0, s[12:13]
	v_cvt_pk_bf16_f32 v36, v44, v45
	v_cvt_pk_bf16_f32 v37, v46, v47
	v_cvt_pk_bf16_f32 v39, v42, v43
	v_lshl_add_u64 v[2:3], v[40:41], 0, v[2:3]
	global_store_dwordx4 v[2:3], v[36:39], off

.LBB0_3554:
	s_andn2_b64 vcc, exec, s[30:31]
	s_cbranch_vccnz .LBB0_3561
	s_and_b32 s4, s10, 1
	s_lshl_b32 s5, s4, 12
	v_add_u32_e32 v1, s5, v230
	v_lshl_add_u32 v2, s4, 10, v229
	s_waitcnt lgkmcnt(0)
	ds_read2st64_b32 v[182:183], v1 offset0:4 offset1:5
	ds_read2st64_b32 v[180:181], v1 offset0:6 offset1:7
	ds_read_b128 v[128:131], v2
	ds_read_b128 v[112:115], v2 offset:16
	ds_read_b128 v[124:127], v2 offset:512
	ds_read_b128 v[108:111], v2 offset:528
	s_and_b64 vcc, exec, s[52:53]
	v_lshlrev_b32_e32 v2, 1, v206
	s_mov_b32 s98, 0x3fb8aa3b
	s_mov_b32 s99, 0x3fb8aa3b
	s_mov_b32 s100, 0x3f317218
	s_mov_b32 s101, 0x3f317218
	s_waitcnt lgkmcnt(0)
	v_pk_mul_f32 v[128:129], v[128:129], s[98:99]
	v_pk_mul_f32 v[130:131], v[130:131], s[98:99]
	v_pk_mul_f32 v[112:113], v[112:113], s[98:99]
	v_pk_mul_f32 v[114:115], v[114:115], s[98:99]
	v_pk_mul_f32 v[124:125], v[124:125], s[100:101]
	v_pk_mul_f32 v[126:127], v[126:127], s[100:101]
	v_pk_mul_f32 v[108:109], v[108:109], s[100:101]
	v_pk_mul_f32 v[110:111], v[110:111], s[100:101]
	s_cbranch_vccz .LBB0_3557
	ds_read2st64_b32 v[184:185], v1 offset1:1
	v_cvt_f32_i32_e32 v187, v177
	v_cvt_f32_i32_e32 v186, v176
	ds_read2st64_b32 v[176:177], v1 offset0:2 offset1:3
	v_cvt_f32_i32_e32 v179, v179
	s_waitcnt lgkmcnt(0)
	v_pk_mul_f32 v[188:189], v[128:129], v[184:185] op_sel_hi:[1,0]
	v_cvt_f32_i32_e32 v178, v178
	v_pk_mul_f32 v[186:187], v[188:189], v[186:187]
	v_pk_mul_f32 v[192:193], v[130:131], v[184:185] op_sel_hi:[1,0]
	v_exp_f32_e64 v1, -v186
	v_exp_f32_e64 v3, -v187
	v_pk_mul_f32 v[178:179], v[192:193], v[178:179]
	v_add_f32_e32 v1, 1.0, v1
	v_rcp_f32_e32 v188, v1
	v_add_f32_e32 v1, 1.0, v3
	v_rcp_f32_e32 v189, v1
	v_cvt_f32_i32_e32 v173, v173
	v_cvt_f32_i32_e32 v172, v172
	v_exp_f32_e64 v1, -v178
	v_pk_mul_f32 v[190:191], v[124:125], v[184:185] op_sel_hi:[1,0]
	v_pk_mul_f32 v[186:187], v[186:187], v[188:189]
	v_pk_mul_f32 v[172:173], v[190:191], v[172:173]
	v_add_f32_e32 v1, 1.0, v1
	v_pk_mul_f32 v[172:173], v[172:173], v[186:187]
	v_rcp_f32_e32 v186, v1
	v_exp_f32_e64 v1, -v179
	v_cvt_f32_i32_e32 v169, v169
	v_cvt_f32_i32_e32 v168, v168
	v_pk_mul_f32 v[190:191], v[112:113], v[184:185] op_sel_hi:[1,0]
	v_add_f32_e32 v1, 1.0, v1
	v_rcp_f32_e32 v187, v1
	v_pk_mul_f32 v[168:169], v[190:191], v[168:169]
	v_cvt_f32_i32_e32 v175, v175
	v_cvt_f32_i32_e32 v174, v174
	v_exp_f32_e64 v1, -v168
	v_pk_mul_f32 v[188:189], v[126:127], v[184:185] op_sel_hi:[1,0]
	v_pk_mul_f32 v[178:179], v[178:179], v[186:187]
	v_pk_mul_f32 v[174:175], v[188:189], v[174:175]
	v_add_f32_e32 v1, 1.0, v1
	v_pk_mul_f32 v[174:175], v[174:175], v[178:179]
	v_rcp_f32_e32 v178, v1
	v_exp_f32_e64 v1, -v169
	v_cvt_f32_i32_e32 v171, v171
	v_cvt_f32_i32_e32 v170, v170
	v_pk_mul_f32 v[186:187], v[114:115], v[184:185] op_sel_hi:[1,0]
	v_add_f32_e32 v1, 1.0, v1
	v_rcp_f32_e32 v179, v1
	v_pk_mul_f32 v[170:171], v[186:187], v[170:171]
	v_cvt_f32_i32_e32 v165, v165
	v_exp_f32_e64 v1, -v170
	v_exp_f32_e64 v3, -v171
	v_cvt_f32_i32_e32 v164, v164
	v_add_f32_e32 v1, 1.0, v1
	v_pk_mul_f32 v[168:169], v[168:169], v[178:179]
	v_rcp_f32_e32 v178, v1
	v_add_f32_e32 v1, 1.0, v3
	v_cvt_f32_i32_e32 v167, v167
	v_cvt_f32_i32_e32 v166, v166
	v_rcp_f32_e32 v179, v1
	v_pk_mul_f32 v[186:187], v[108:109], v[184:185] op_sel_hi:[1,0]
	v_cvt_f32_i32_e32 v161, v161
	v_pk_mul_f32 v[164:165], v[186:187], v[164:165]
	v_cvt_f32_i32_e32 v160, v160
	v_pk_mul_f32 v[164:165], v[164:165], v[168:169]
	v_pk_mul_f32 v[168:169], v[110:111], v[184:185] op_sel_hi:[1,0]
	s_lshl_b32 s37, s50, 8
	v_pk_mul_f32 v[166:167], v[168:169], v[166:167]
	v_pk_mul_f32 v[168:169], v[170:171], v[178:179]
	v_add_u32_e32 v1, s37, v221
	v_pk_mul_f32 v[170:171], v[166:167], v[168:169]
	v_cvt_pk_bf16_f32 v166, v172, v173
	v_mov_b32_e32 v172, v185
	v_cvt_pk_bf16_f32 v167, v174, v175
	v_cvt_pk_bf16_f32 v168, v164, v165
	v_mov_b64_e32 v[164:165], s[28:29]
	v_pk_mul_f32 v[174:175], v[128:129], v[172:173] op_sel_hi:[1,0]
	v_cvt_pk_bf16_f32 v169, v170, v171
	v_mad_i64_i32 v[170:171], s[4:5], v1, s66, v[164:165]
	v_pk_mul_f32 v[160:161], v[174:175], v[160:161]
	s_lshl_b32 s4, s48, 7
	s_ashr_i32 s5, s4, 31
	v_exp_f32_e64 v1, -v160
	s_lshl_b64 s[6:7], s[4:5], 1
	v_lshl_add_u64 v[170:171], v[170:171], 0, s[6:7]
	s_lshl_b32 s10, s79, 1
	v_lshl_add_u64 v[170:171], v[170:171], 0, s[10:11]
	v_mov_b32_e32 v3, v0
	v_lshl_add_u64 v[170:171], v[170:171], 0, v[2:3]
	v_add_f32_e32 v1, 1.0, v1
	global_store_dwordx4 v[170:171], v[166:169], off
	v_cvt_f32_i32_e32 v163, v163
	v_cvt_f32_i32_e32 v162, v162
	v_rcp_f32_e32 v166, v1
	v_exp_f32_e64 v1, -v161
	v_pk_mul_f32 v[170:171], v[130:131], v[172:173] op_sel_hi:[1,0]
	v_cvt_f32_i32_e32 v157, v157
	v_pk_mul_f32 v[162:163], v[170:171], v[162:163]
	v_add_f32_e32 v1, 1.0, v1
	v_rcp_f32_e32 v167, v1
	v_cvt_f32_i32_e32 v156, v156
	v_exp_f32_e64 v1, -v162
	v_pk_mul_f32 v[168:169], v[124:125], v[172:173] op_sel_hi:[1,0]
	v_pk_mul_f32 v[160:161], v[160:161], v[166:167]
	v_pk_mul_f32 v[156:157], v[168:169], v[156:157]
	v_add_f32_e32 v1, 1.0, v1
	v_pk_mul_f32 v[156:157], v[156:157], v[160:161]
	v_rcp_f32_e32 v160, v1
	v_exp_f32_e64 v1, -v163
	v_cvt_f32_i32_e32 v153, v153
	v_cvt_f32_i32_e32 v152, v152
	v_pk_mul_f32 v[168:169], v[112:113], v[172:173] op_sel_hi:[1,0]
	v_add_f32_e32 v1, 1.0, v1
	v_rcp_f32_e32 v161, v1
	v_pk_mul_f32 v[152:153], v[168:169], v[152:153]
	v_cvt_f32_i32_e32 v159, v159
	v_cvt_f32_i32_e32 v158, v158
	v_exp_f32_e64 v1, -v152
	v_pk_mul_f32 v[166:167], v[126:127], v[172:173] op_sel_hi:[1,0]
	v_pk_mul_f32 v[160:161], v[162:163], v[160:161]
	v_pk_mul_f32 v[158:159], v[166:167], v[158:159]
	v_add_f32_e32 v1, 1.0, v1
	v_pk_mul_f32 v[158:159], v[158:159], v[160:161]
	v_rcp_f32_e32 v160, v1
	v_exp_f32_e64 v1, -v153
	v_cvt_f32_i32_e32 v155, v155
	v_cvt_f32_i32_e32 v154, v154
	v_pk_mul_f32 v[162:163], v[114:115], v[172:173] op_sel_hi:[1,0]
	v_add_f32_e32 v1, 1.0, v1
	v_rcp_f32_e32 v161, v1
	v_pk_mul_f32 v[154:155], v[162:163], v[154:155]
	v_cvt_f32_i32_e32 v149, v149
	v_exp_f32_e64 v1, -v154
	v_pk_mul_f32 v[152:153], v[152:153], v[160:161]
	v_exp_f32_e64 v161, -v155
	v_cvt_f32_i32_e32 v148, v148
	v_add_f32_e32 v1, 1.0, v1
	v_rcp_f32_e32 v160, v1
	v_add_f32_e32 v1, 1.0, v161
	v_cvt_f32_i32_e32 v151, v151
	v_cvt_f32_i32_e32 v150, v150
	v_rcp_f32_e32 v161, v1
	v_pk_mul_f32 v[162:163], v[108:109], v[172:173] op_sel_hi:[1,0]
	v_cvt_f32_i32_e32 v145, v145
	v_pk_mul_f32 v[148:149], v[162:163], v[148:149]
	v_cvt_f32_i32_e32 v144, v144
	v_pk_mul_f32 v[152:153], v[148:149], v[152:153]
	v_pk_mul_f32 v[148:149], v[110:111], v[172:173] op_sel_hi:[1,0]
	v_add_u32_e32 v1, s37, v222
	v_pk_mul_f32 v[148:149], v[148:149], v[150:151]
	v_pk_mul_f32 v[150:151], v[154:155], v[160:161]
	v_cvt_f32_i32_e32 v147, v147
	v_pk_mul_f32 v[154:155], v[148:149], v[150:151]
	v_cvt_pk_bf16_f32 v150, v152, v153
	v_cvt_pk_bf16_f32 v151, v154, v155
	v_pk_mul_f32 v[154:155], v[128:129], v[176:177] op_sel_hi:[1,0]
	v_mad_i64_i32 v[152:153], s[52:53], v1, s66, v[164:165]
	v_pk_mul_f32 v[144:145], v[154:155], v[144:145]
	v_lshl_add_u64 v[152:153], v[152:153], 0, s[6:7]
	v_exp_f32_e64 v1, -v144
	v_lshl_add_u64 v[152:153], v[152:153], 0, s[10:11]
	v_cvt_pk_bf16_f32 v148, v156, v157
	v_cvt_pk_bf16_f32 v149, v158, v159
	v_lshl_add_u64 v[152:153], v[152:153], 0, v[2:3]
	v_add_f32_e32 v1, 1.0, v1
	global_store_dwordx4 v[152:153], v[148:151], off
	v_cvt_f32_i32_e32 v146, v146
	v_pk_mul_f32 v[152:153], v[130:131], v[176:177] op_sel_hi:[1,0]
	v_rcp_f32_e32 v148, v1
	v_exp_f32_e64 v1, -v145
	v_pk_mul_f32 v[146:147], v[152:153], v[146:147]
	v_cvt_f32_i32_e32 v141, v141
	v_cvt_f32_i32_e32 v140, v140
	v_add_f32_e32 v1, 1.0, v1
	v_rcp_f32_e32 v149, v1
	v_exp_f32_e64 v1, -v146
	v_pk_mul_f32 v[150:151], v[124:125], v[176:177] op_sel_hi:[1,0]
	v_pk_mul_f32 v[144:145], v[144:145], v[148:149]
	v_pk_mul_f32 v[140:141], v[150:151], v[140:141]
	v_add_f32_e32 v1, 1.0, v1
	v_pk_mul_f32 v[140:141], v[140:141], v[144:145]
	v_rcp_f32_e32 v144, v1
	v_exp_f32_e64 v1, -v147
	v_cvt_f32_i32_e32 v137, v137
	v_cvt_f32_i32_e32 v136, v136
	v_pk_mul_f32 v[150:151], v[112:113], v[176:177] op_sel_hi:[1,0]
	v_add_f32_e32 v1, 1.0, v1
	v_rcp_f32_e32 v145, v1
	v_pk_mul_f32 v[136:137], v[150:151], v[136:137]
	v_cvt_f32_i32_e32 v143, v143
	v_cvt_f32_i32_e32 v142, v142
	v_exp_f32_e64 v1, -v136
	v_pk_mul_f32 v[148:149], v[126:127], v[176:177] op_sel_hi:[1,0]
	v_pk_mul_f32 v[144:145], v[146:147], v[144:145]
	v_pk_mul_f32 v[142:143], v[148:149], v[142:143]
	v_add_f32_e32 v1, 1.0, v1
	v_pk_mul_f32 v[142:143], v[142:143], v[144:145]
	v_rcp_f32_e32 v144, v1
	v_exp_f32_e64 v1, -v137
	v_cvt_f32_i32_e32 v139, v139
	v_cvt_f32_i32_e32 v138, v138
	v_pk_mul_f32 v[146:147], v[114:115], v[176:177] op_sel_hi:[1,0]
	v_add_f32_e32 v1, 1.0, v1
	v_rcp_f32_e32 v145, v1
	v_pk_mul_f32 v[138:139], v[146:147], v[138:139]
	v_cvt_f32_i32_e32 v133, v133
	v_exp_f32_e64 v1, -v138
	v_pk_mul_f32 v[136:137], v[136:137], v[144:145]
	v_exp_f32_e64 v145, -v139
	v_cvt_f32_i32_e32 v132, v132
	v_add_f32_e32 v1, 1.0, v1
	v_rcp_f32_e32 v144, v1
	v_add_f32_e32 v1, 1.0, v145
	v_cvt_f32_i32_e32 v135, v135
	v_cvt_f32_i32_e32 v134, v134
	v_rcp_f32_e32 v145, v1
	v_pk_mul_f32 v[146:147], v[108:109], v[176:177] op_sel_hi:[1,0]
	v_cvt_f32_i32_e32 v121, v121
	v_pk_mul_f32 v[132:133], v[146:147], v[132:133]
	v_cvt_f32_i32_e32 v120, v120
	v_pk_mul_f32 v[136:137], v[132:133], v[136:137]
	v_pk_mul_f32 v[132:133], v[110:111], v[176:177] op_sel_hi:[1,0]
	v_add_u32_e32 v1, s37, v223
	v_pk_mul_f32 v[132:133], v[132:133], v[134:135]
	v_pk_mul_f32 v[134:135], v[138:139], v[144:145]
	v_cvt_f32_i32_e32 v123, v123
	v_pk_mul_f32 v[138:139], v[132:133], v[134:135]
	v_cvt_pk_bf16_f32 v132, v140, v141
	v_cvt_pk_bf16_f32 v135, v138, v139
	v_mov_b32_e32 v138, v177
	v_pk_mul_f32 v[140:141], v[128:129], v[138:139] op_sel_hi:[1,0]
	v_cvt_pk_bf16_f32 v134, v136, v137
	v_pk_mul_f32 v[120:121], v[140:141], v[120:121]
	v_mad_i64_i32 v[136:137], s[52:53], v1, s66, v[164:165]
	v_exp_f32_e64 v1, -v120
	v_lshl_add_u64 v[136:137], v[136:137], 0, s[6:7]
	v_lshl_add_u64 v[136:137], v[136:137], 0, s[10:11]
	v_cvt_pk_bf16_f32 v133, v142, v143
	v_lshl_add_u64 v[136:137], v[136:137], 0, v[2:3]
	v_add_f32_e32 v1, 1.0, v1
	global_store_dwordx4 v[136:137], v[132:135], off
	v_cvt_f32_i32_e32 v122, v122
	v_pk_mul_f32 v[136:137], v[130:131], v[138:139] op_sel_hi:[1,0]
	v_rcp_f32_e32 v132, v1
	v_exp_f32_e64 v1, -v121
	v_pk_mul_f32 v[122:123], v[136:137], v[122:123]
	v_cvt_f32_i32_e32 v117, v117
	v_cvt_f32_i32_e32 v116, v116
	v_add_f32_e32 v1, 1.0, v1
	v_rcp_f32_e32 v133, v1
	v_exp_f32_e64 v1, -v122
	v_pk_mul_f32 v[134:135], v[124:125], v[138:139] op_sel_hi:[1,0]
	v_pk_mul_f32 v[120:121], v[120:121], v[132:133]
	v_pk_mul_f32 v[116:117], v[134:135], v[116:117]
	v_add_f32_e32 v1, 1.0, v1
	v_pk_mul_f32 v[116:117], v[116:117], v[120:121]
	v_rcp_f32_e32 v120, v1
	v_exp_f32_e64 v1, -v123
	v_cvt_f32_i32_e32 v105, v105
	v_cvt_f32_i32_e32 v104, v104
	v_pk_mul_f32 v[134:135], v[112:113], v[138:139] op_sel_hi:[1,0]
	v_add_f32_e32 v1, 1.0, v1
	v_rcp_f32_e32 v121, v1
	v_pk_mul_f32 v[104:105], v[134:135], v[104:105]
	v_cvt_f32_i32_e32 v119, v119
	v_cvt_f32_i32_e32 v118, v118
	v_exp_f32_e64 v1, -v104
	v_pk_mul_f32 v[132:133], v[126:127], v[138:139] op_sel_hi:[1,0]
	v_pk_mul_f32 v[120:121], v[122:123], v[120:121]
	v_pk_mul_f32 v[118:119], v[132:133], v[118:119]
	v_add_f32_e32 v1, 1.0, v1
	v_pk_mul_f32 v[118:119], v[118:119], v[120:121]
	v_rcp_f32_e32 v120, v1
	v_exp_f32_e64 v1, -v105
	v_cvt_f32_i32_e32 v107, v107
	v_cvt_f32_i32_e32 v106, v106
	v_pk_mul_f32 v[122:123], v[114:115], v[138:139] op_sel_hi:[1,0]
	v_add_f32_e32 v1, 1.0, v1
	v_rcp_f32_e32 v121, v1
	v_pk_mul_f32 v[106:107], v[122:123], v[106:107]
	v_cvt_f32_i32_e32 v101, v101
	v_exp_f32_e64 v1, -v106
	v_pk_mul_f32 v[104:105], v[104:105], v[120:121]
	v_exp_f32_e64 v121, -v107
	v_cvt_f32_i32_e32 v100, v100
	v_add_f32_e32 v1, 1.0, v1
	v_rcp_f32_e32 v120, v1
	v_add_f32_e32 v1, 1.0, v121
	v_cvt_f32_i32_e32 v103, v103
	v_cvt_f32_i32_e32 v102, v102
	v_rcp_f32_e32 v121, v1
	v_pk_mul_f32 v[122:123], v[108:109], v[138:139] op_sel_hi:[1,0]
	v_add_u32_e32 v1, s37, v224
	v_pk_mul_f32 v[100:101], v[122:123], v[100:101]
	s_nop 0
	v_pk_mul_f32 v[104:105], v[100:101], v[104:105]
	v_pk_mul_f32 v[100:101], v[110:111], v[138:139] op_sel_hi:[1,0]
	s_nop 0
	v_pk_mul_f32 v[100:101], v[100:101], v[102:103]
	v_pk_mul_f32 v[102:103], v[106:107], v[120:121]
	s_nop 0
	v_pk_mul_f32 v[106:107], v[100:101], v[102:103]
	v_cvt_pk_bf16_f32 v102, v104, v105
	v_mad_i64_i32 v[104:105], s[52:53], v1, s66, v[164:165]
	v_lshl_add_u64 v[104:105], v[104:105], 0, s[6:7]
	v_lshl_add_u64 v[104:105], v[104:105], 0, s[10:11]
	v_cvt_pk_bf16_f32 v100, v116, v117
	v_cvt_pk_bf16_f32 v101, v118, v119
	v_cvt_pk_bf16_f32 v103, v106, v107
	v_lshl_add_u64 v[104:105], v[104:105], 0, v[2:3]
	global_store_dwordx4 v[104:105], v[100:103], off
	s_cbranch_execz .LBB0_3558
	s_branch .LBB0_3559

.LBB0_3559:
	s_andn2_b64 vcc, exec, s[0:1]
	s_cbranch_vccnz .LBB0_3561
	v_cvt_f32_i32_e32 v97, v97
	v_cvt_f32_i32_e32 v96, v96
	s_waitcnt lgkmcnt(0)
	v_pk_mul_f32 v[100:101], v[182:183], v[128:129] op_sel_hi:[0,1]
	v_cvt_f32_i32_e32 v93, v93
	v_cvt_f32_i32_e32 v92, v92
	v_pk_mul_f32 v[96:97], v[100:101], v[96:97]
	v_cvt_f32_i32_e32 v99, v99
	v_exp_f32_e64 v1, -v96
	v_cvt_f32_i32_e32 v98, v98
	v_pk_mul_f32 v[102:103], v[182:183], v[124:125] op_sel_hi:[0,1]
	v_add_f32_e32 v1, 1.0, v1
	v_rcp_f32_e32 v100, v1
	v_exp_f32_e64 v1, -v97
	v_pk_mul_f32 v[92:93], v[102:103], v[92:93]
	v_pk_mul_f32 v[102:103], v[182:183], v[130:131] op_sel_hi:[0,1]
	v_pk_mul_f32 v[98:99], v[102:103], v[98:99]
	v_add_f32_e32 v1, 1.0, v1
	v_rcp_f32_e32 v101, v1
	v_exp_f32_e64 v1, -v98
	v_cvt_f32_i32_e32 v89, v89
	v_pk_mul_f32 v[96:97], v[96:97], v[100:101]
	v_cvt_f32_i32_e32 v88, v88
	v_add_f32_e32 v1, 1.0, v1
	v_rcp_f32_e32 v100, v1
	v_exp_f32_e64 v1, -v99
	v_pk_mul_f32 v[102:103], v[182:183], v[112:113] op_sel_hi:[0,1]
	v_pk_mul_f32 v[88:89], v[102:103], v[88:89]
	v_cvt_f32_i32_e32 v95, v95
	v_add_f32_e32 v1, 1.0, v1
	v_rcp_f32_e32 v101, v1
	v_cvt_f32_i32_e32 v94, v94
	v_exp_f32_e64 v1, -v88
	v_pk_mul_f32 v[92:93], v[92:93], v[96:97]
	v_pk_mul_f32 v[96:97], v[182:183], v[126:127] op_sel_hi:[0,1]
	v_pk_mul_f32 v[94:95], v[96:97], v[94:95]
	v_pk_mul_f32 v[96:97], v[98:99], v[100:101]
	v_add_f32_e32 v1, 1.0, v1
	v_pk_mul_f32 v[94:95], v[94:95], v[96:97]
	v_rcp_f32_e32 v96, v1
	v_exp_f32_e64 v1, -v89
	v_cvt_f32_i32_e32 v91, v91
	v_cvt_f32_i32_e32 v90, v90
	v_pk_mul_f32 v[98:99], v[182:183], v[114:115] op_sel_hi:[0,1]
	v_add_f32_e32 v1, 1.0, v1
	v_rcp_f32_e32 v97, v1
	v_pk_mul_f32 v[90:91], v[98:99], v[90:91]
	v_cvt_f32_i32_e32 v85, v85
	v_exp_f32_e64 v1, -v90
	v_exp_f32_e64 v3, -v91
	v_cvt_f32_i32_e32 v84, v84
	v_add_f32_e32 v1, 1.0, v1
	v_pk_mul_f32 v[88:89], v[88:89], v[96:97]
	v_rcp_f32_e32 v96, v1
	v_add_f32_e32 v1, 1.0, v3
	v_cvt_f32_i32_e32 v87, v87
	v_cvt_f32_i32_e32 v86, v86
	v_rcp_f32_e32 v97, v1
	v_pk_mul_f32 v[98:99], v[182:183], v[108:109] op_sel_hi:[0,1]
	v_pk_mul_f32 v[84:85], v[98:99], v[84:85]
	v_cvt_f32_i32_e32 v81, v81
	v_pk_mul_f32 v[84:85], v[84:85], v[88:89]
	v_pk_mul_f32 v[88:89], v[182:183], v[110:111] op_sel_hi:[0,1]
	v_cvt_f32_i32_e32 v80, v80
	v_pk_mul_f32 v[86:87], v[88:89], v[86:87]
	v_pk_mul_f32 v[88:89], v[90:91], v[96:97]
	v_add_u32_e32 v1, s37, v225
	v_pk_mul_f32 v[90:91], v[86:87], v[88:89]
	v_cvt_pk_bf16_f32 v86, v92, v93
	v_mov_b32_e32 v92, v183
	v_cvt_pk_bf16_f32 v87, v94, v95
	v_pk_mul_f32 v[94:95], v[92:93], v[128:129] op_sel_hi:[0,1]
	v_cvt_pk_bf16_f32 v88, v84, v85
	v_mov_b64_e32 v[84:85], s[28:29]
	v_pk_mul_f32 v[80:81], v[94:95], v[80:81]
	v_cvt_pk_bf16_f32 v89, v90, v91
	v_mad_i64_i32 v[90:91], s[0:1], v1, s66, v[84:85]
	v_exp_f32_e64 v1, -v80
	s_lshl_b64 s[0:1], s[4:5], 1
	v_lshl_add_u64 v[90:91], v[90:91], 0, s[0:1]
	s_lshl_b32 s10, s79, 1
	v_lshl_add_u64 v[90:91], v[90:91], 0, s[10:11]
	v_mov_b32_e32 v3, v0
	v_lshl_add_u64 v[90:91], v[90:91], 0, v[2:3]
	v_add_f32_e32 v1, 1.0, v1
	global_store_dwordx4 v[90:91], v[86:89], off
	v_cvt_f32_i32_e32 v83, v83
	v_cvt_f32_i32_e32 v82, v82
	v_rcp_f32_e32 v86, v1
	v_exp_f32_e64 v1, -v81
	v_pk_mul_f32 v[90:91], v[92:93], v[130:131] op_sel_hi:[0,1]
	v_pk_mul_f32 v[82:83], v[90:91], v[82:83]
	v_cvt_f32_i32_e32 v77, v77
	v_add_f32_e32 v1, 1.0, v1
	v_rcp_f32_e32 v87, v1
	v_cvt_f32_i32_e32 v76, v76
	v_exp_f32_e64 v1, -v82
	v_pk_mul_f32 v[88:89], v[92:93], v[124:125] op_sel_hi:[0,1]
	v_pk_mul_f32 v[80:81], v[80:81], v[86:87]
	v_pk_mul_f32 v[76:77], v[88:89], v[76:77]
	v_add_f32_e32 v1, 1.0, v1
	v_pk_mul_f32 v[76:77], v[76:77], v[80:81]
	v_rcp_f32_e32 v80, v1
	v_exp_f32_e64 v1, -v83
	v_cvt_f32_i32_e32 v73, v73
	v_cvt_f32_i32_e32 v72, v72
	v_pk_mul_f32 v[88:89], v[92:93], v[112:113] op_sel_hi:[0,1]
	v_add_f32_e32 v1, 1.0, v1
	v_rcp_f32_e32 v81, v1
	v_pk_mul_f32 v[72:73], v[88:89], v[72:73]
	v_cvt_f32_i32_e32 v79, v79
	v_cvt_f32_i32_e32 v78, v78
	v_exp_f32_e64 v1, -v72
	v_pk_mul_f32 v[86:87], v[92:93], v[126:127] op_sel_hi:[0,1]
	v_pk_mul_f32 v[80:81], v[82:83], v[80:81]
	v_pk_mul_f32 v[78:79], v[86:87], v[78:79]
	v_add_f32_e32 v1, 1.0, v1
	v_pk_mul_f32 v[78:79], v[78:79], v[80:81]
	v_rcp_f32_e32 v80, v1
	v_exp_f32_e64 v1, -v73
	v_cvt_f32_i32_e32 v75, v75
	v_cvt_f32_i32_e32 v74, v74
	v_pk_mul_f32 v[82:83], v[92:93], v[114:115] op_sel_hi:[0,1]
	v_add_f32_e32 v1, 1.0, v1
	v_rcp_f32_e32 v81, v1
	v_pk_mul_f32 v[74:75], v[82:83], v[74:75]
	v_cvt_f32_i32_e32 v69, v69
	v_exp_f32_e64 v1, -v74
	v_pk_mul_f32 v[72:73], v[72:73], v[80:81]
	v_exp_f32_e64 v81, -v75
	v_cvt_f32_i32_e32 v68, v68
	v_add_f32_e32 v1, 1.0, v1
	v_rcp_f32_e32 v80, v1
	v_add_f32_e32 v1, 1.0, v81
	v_cvt_f32_i32_e32 v71, v71
	v_cvt_f32_i32_e32 v70, v70
	v_rcp_f32_e32 v81, v1
	v_pk_mul_f32 v[82:83], v[92:93], v[108:109] op_sel_hi:[0,1]
	v_pk_mul_f32 v[68:69], v[82:83], v[68:69]
	v_cvt_f32_i32_e32 v65, v65
	v_pk_mul_f32 v[72:73], v[68:69], v[72:73]
	v_pk_mul_f32 v[68:69], v[92:93], v[110:111] op_sel_hi:[0,1]
	v_cvt_f32_i32_e32 v64, v64
	v_pk_mul_f32 v[68:69], v[68:69], v[70:71]
	v_pk_mul_f32 v[70:71], v[74:75], v[80:81]
	v_add_u32_e32 v1, s37, v226
	v_pk_mul_f32 v[74:75], v[68:69], v[70:71]
	v_cvt_pk_bf16_f32 v70, v72, v73
	v_cvt_pk_bf16_f32 v71, v74, v75
	v_pk_mul_f32 v[74:75], v[180:181], v[128:129] op_sel_hi:[0,1]
	v_pk_mul_f32 v[64:65], v[74:75], v[64:65]
	v_mad_i64_i32 v[72:73], s[4:5], v1, s66, v[84:85]
	v_exp_f32_e64 v1, -v64
	v_lshl_add_u64 v[72:73], v[72:73], 0, s[0:1]
	v_lshl_add_u64 v[72:73], v[72:73], 0, s[10:11]
	v_cvt_pk_bf16_f32 v68, v76, v77
	v_cvt_pk_bf16_f32 v69, v78, v79
	v_lshl_add_u64 v[72:73], v[72:73], 0, v[2:3]
	v_add_f32_e32 v1, 1.0, v1
	global_store_dwordx4 v[72:73], v[68:71], off
	v_cvt_f32_i32_e32 v67, v67
	v_cvt_f32_i32_e32 v66, v66
	v_rcp_f32_e32 v68, v1
	v_exp_f32_e64 v1, -v65
	v_pk_mul_f32 v[72:73], v[180:181], v[130:131] op_sel_hi:[0,1]
	v_pk_mul_f32 v[66:67], v[72:73], v[66:67]
	v_cvt_f32_i32_e32 v61, v61
	v_add_f32_e32 v1, 1.0, v1
	v_rcp_f32_e32 v69, v1
	v_cvt_f32_i32_e32 v60, v60
	v_exp_f32_e64 v1, -v66
	v_pk_mul_f32 v[70:71], v[180:181], v[124:125] op_sel_hi:[0,1]
	v_pk_mul_f32 v[64:65], v[64:65], v[68:69]
	v_pk_mul_f32 v[60:61], v[70:71], v[60:61]
	v_add_f32_e32 v1, 1.0, v1
	v_pk_mul_f32 v[60:61], v[60:61], v[64:65]
	v_rcp_f32_e32 v64, v1
	v_exp_f32_e64 v1, -v67
	v_cvt_f32_i32_e32 v57, v57
	v_cvt_f32_i32_e32 v56, v56
	v_pk_mul_f32 v[70:71], v[180:181], v[112:113] op_sel_hi:[0,1]
	v_add_f32_e32 v1, 1.0, v1
	v_rcp_f32_e32 v65, v1
	v_pk_mul_f32 v[56:57], v[70:71], v[56:57]
	v_cvt_f32_i32_e32 v63, v63
	v_cvt_f32_i32_e32 v62, v62
	v_exp_f32_e64 v1, -v56
	v_pk_mul_f32 v[68:69], v[180:181], v[126:127] op_sel_hi:[0,1]
	v_pk_mul_f32 v[64:65], v[66:67], v[64:65]
	v_pk_mul_f32 v[62:63], v[68:69], v[62:63]
	v_add_f32_e32 v1, 1.0, v1
	v_pk_mul_f32 v[62:63], v[62:63], v[64:65]
	v_rcp_f32_e32 v64, v1
	v_exp_f32_e64 v1, -v57
	v_cvt_f32_i32_e32 v59, v59
	v_cvt_f32_i32_e32 v58, v58
	v_pk_mul_f32 v[66:67], v[180:181], v[114:115] op_sel_hi:[0,1]
	v_add_f32_e32 v1, 1.0, v1
	v_rcp_f32_e32 v65, v1
	v_pk_mul_f32 v[58:59], v[66:67], v[58:59]
	v_cvt_f32_i32_e32 v53, v53
	v_exp_f32_e64 v1, -v58
	v_pk_mul_f32 v[56:57], v[56:57], v[64:65]
	v_exp_f32_e64 v65, -v59
	v_cvt_f32_i32_e32 v52, v52
	v_add_f32_e32 v1, 1.0, v1
	v_rcp_f32_e32 v64, v1
	v_add_f32_e32 v1, 1.0, v65
	v_cvt_f32_i32_e32 v55, v55
	v_cvt_f32_i32_e32 v54, v54
	v_rcp_f32_e32 v65, v1
	v_pk_mul_f32 v[66:67], v[180:181], v[108:109] op_sel_hi:[0,1]
	v_pk_mul_f32 v[52:53], v[66:67], v[52:53]
	v_cvt_f32_i32_e32 v49, v49
	v_pk_mul_f32 v[56:57], v[52:53], v[56:57]
	v_pk_mul_f32 v[52:53], v[180:181], v[110:111] op_sel_hi:[0,1]
	v_pk_mul_f32 v[52:53], v[52:53], v[54:55]
	v_pk_mul_f32 v[54:55], v[58:59], v[64:65]
	v_cvt_f32_i32_e32 v48, v48
	v_pk_mul_f32 v[58:59], v[52:53], v[54:55]
	v_cvt_pk_bf16_f32 v52, v60, v61
	v_cvt_pk_bf16_f32 v55, v58, v59
	v_mov_b32_e32 v58, v181
	v_pk_mul_f32 v[60:61], v[58:59], v[128:129] op_sel_hi:[0,1]
	v_add_u32_e32 v1, s37, v227
	v_pk_mul_f32 v[48:49], v[60:61], v[48:49]
	v_cvt_pk_bf16_f32 v54, v56, v57
	v_mad_i64_i32 v[56:57], s[4:5], v1, s66, v[84:85]
	v_exp_f32_e64 v1, -v48
	v_lshl_add_u64 v[56:57], v[56:57], 0, s[0:1]
	v_lshl_add_u64 v[56:57], v[56:57], 0, s[10:11]
	v_cvt_pk_bf16_f32 v53, v62, v63
	v_lshl_add_u64 v[56:57], v[56:57], 0, v[2:3]
	v_add_f32_e32 v1, 1.0, v1
	global_store_dwordx4 v[56:57], v[52:55], off
	v_cvt_f32_i32_e32 v51, v51
	v_cvt_f32_i32_e32 v50, v50
	v_rcp_f32_e32 v52, v1
	v_exp_f32_e64 v1, -v49
	v_pk_mul_f32 v[56:57], v[58:59], v[130:131] op_sel_hi:[0,1]
	v_pk_mul_f32 v[50:51], v[56:57], v[50:51]
	v_cvt_f32_i32_e32 v45, v45
	v_add_f32_e32 v1, 1.0, v1
	v_rcp_f32_e32 v53, v1
	v_cvt_f32_i32_e32 v44, v44
	v_exp_f32_e64 v1, -v50
	v_pk_mul_f32 v[54:55], v[58:59], v[124:125] op_sel_hi:[0,1]
	v_pk_mul_f32 v[48:49], v[48:49], v[52:53]
	v_pk_mul_f32 v[44:45], v[54:55], v[44:45]
	v_add_f32_e32 v1, 1.0, v1
	v_pk_mul_f32 v[44:45], v[44:45], v[48:49]
	v_rcp_f32_e32 v48, v1
	v_exp_f32_e64 v1, -v51
	v_cvt_f32_i32_e32 v41, v41
	v_cvt_f32_i32_e32 v40, v40
	v_pk_mul_f32 v[54:55], v[58:59], v[112:113] op_sel_hi:[0,1]
	v_add_f32_e32 v1, 1.0, v1
	v_rcp_f32_e32 v49, v1
	v_pk_mul_f32 v[40:41], v[54:55], v[40:41]
	v_cvt_f32_i32_e32 v47, v47
	v_cvt_f32_i32_e32 v46, v46
	v_exp_f32_e64 v1, -v40
	v_pk_mul_f32 v[52:53], v[58:59], v[126:127] op_sel_hi:[0,1]
	v_pk_mul_f32 v[48:49], v[50:51], v[48:49]
	v_pk_mul_f32 v[46:47], v[52:53], v[46:47]
	v_add_f32_e32 v1, 1.0, v1
	v_pk_mul_f32 v[46:47], v[46:47], v[48:49]
	v_rcp_f32_e32 v48, v1
	v_exp_f32_e64 v1, -v41
	v_cvt_f32_i32_e32 v43, v43
	v_cvt_f32_i32_e32 v42, v42
	v_pk_mul_f32 v[50:51], v[58:59], v[114:115] op_sel_hi:[0,1]
	v_add_f32_e32 v1, 1.0, v1
	v_rcp_f32_e32 v49, v1
	v_pk_mul_f32 v[42:43], v[50:51], v[42:43]
	v_cvt_f32_i32_e32 v37, v37
	v_exp_f32_e64 v1, -v42
	v_pk_mul_f32 v[40:41], v[40:41], v[48:49]
	v_exp_f32_e64 v49, -v43
	v_cvt_f32_i32_e32 v36, v36
	v_add_f32_e32 v1, 1.0, v1
	v_rcp_f32_e32 v48, v1
	v_add_f32_e32 v1, 1.0, v49
	v_cvt_f32_i32_e32 v39, v39
	v_cvt_f32_i32_e32 v38, v38
	v_rcp_f32_e32 v49, v1
	v_pk_mul_f32 v[50:51], v[58:59], v[108:109] op_sel_hi:[0,1]
	v_pk_mul_f32 v[36:37], v[50:51], v[36:37]
	v_add_u32_e32 v1, s37, v228
	v_pk_mul_f32 v[40:41], v[36:37], v[40:41]
	v_pk_mul_f32 v[36:37], v[58:59], v[110:111] op_sel_hi:[0,1]
	v_pk_mul_f32 v[36:37], v[36:37], v[38:39]
	v_pk_mul_f32 v[38:39], v[42:43], v[48:49]
	s_nop 0
	v_pk_mul_f32 v[42:43], v[36:37], v[38:39]
	v_cvt_pk_bf16_f32 v38, v40, v41
	v_mad_i64_i32 v[40:41], s[4:5], v1, s66, v[84:85]
	v_lshl_add_u64 v[40:41], v[40:41], 0, s[0:1]
	v_lshl_add_u64 v[40:41], v[40:41], 0, s[10:11]
	v_cvt_pk_bf16_f32 v36, v44, v45
	v_cvt_pk_bf16_f32 v37, v46, v47
	v_cvt_pk_bf16_f32 v39, v42, v43
	v_lshl_add_u64 v[2:3], v[40:41], 0, v[2:3]
	global_store_dwordx4 v[2:3], v[36:39], off

	.amdhsa_kernel _Z8mega_fwd6Params
		.amdhsa_group_segment_fixed_size 0
		.amdhsa_private_segment_fixed_size 0
		.amdhsa_kernarg_size 536
		.amdhsa_user_sgpr_count 2
		.amdhsa_user_sgpr_dispatch_ptr 0
		.amdhsa_user_sgpr_queue_ptr 0
		.amdhsa_user_sgpr_kernarg_segment_ptr 1
		.amdhsa_user_sgpr_dispatch_id 0
		.amdhsa_user_sgpr_kernarg_preload_length 0
		.amdhsa_user_sgpr_kernarg_preload_offset 0
		.amdhsa_user_sgpr_private_segment_size 0
		.amdhsa_uses_dynamic_stack 0
		.amdhsa_enable_private_segment 0
		.amdhsa_system_sgpr_workgroup_id_x 1
		.amdhsa_system_sgpr_workgroup_id_y 0
		.amdhsa_system_sgpr_workgroup_id_z 0
		.amdhsa_system_sgpr_workgroup_info 0
		.amdhsa_system_vgpr_workitem_id 2
		.amdhsa_next_free_vgpr 255
		.amdhsa_next_free_sgpr 102
		.amdhsa_accum_offset 256
		.amdhsa_reserve_vcc 1
		.amdhsa_float_round_mode_32 0
		.amdhsa_float_round_mode_16_64 0
		.amdhsa_float_denorm_mode_32 3
		.amdhsa_float_denorm_mode_16_64 3
		.amdhsa_dx10_clamp 1
		.amdhsa_ieee_mode 1
		.amdhsa_fp16_overflow 0
		.amdhsa_tg_split 0
		.amdhsa_exception_fp_ieee_invalid_op 0
		.amdhsa_exception_fp_denorm_src 0
		.amdhsa_exception_fp_ieee_div_zero 0
		.amdhsa_exception_fp_ieee_overflow 0
		.amdhsa_exception_fp_ieee_underflow 0
		.amdhsa_exception_fp_ieee_inexact 0
		.amdhsa_exception_int_div_zero 0
	.end_amdhsa_kernel

amdhsa.kernels:
  - .agpr_count:     0
    .args:
      - .offset:         0
        .size:           280
        .value_kind:     by_value
      - .offset:         280
        .size:           4
        .value_kind:     hidden_block_count_x
      - .offset:         284
        .size:           4
        .value_kind:     hidden_block_count_y
      - .offset:         288
        .size:           4
        .value_kind:     hidden_block_count_z
      - .offset:         292
        .size:           2
        .value_kind:     hidden_group_size_x
      - .offset:         294
        .size:           2
        .value_kind:     hidden_group_size_y
      - .offset:         296
        .size:           2
        .value_kind:     hidden_group_size_z
      - .offset:         298
        .size:           2
        .value_kind:     hidden_remainder_x
      - .offset:         300
        .size:           2
        .value_kind:     hidden_remainder_y
      - .offset:         302
        .size:           2
        .value_kind:     hidden_remainder_z
      - .offset:         320
        .size:           8
        .value_kind:     hidden_global_offset_x
      - .offset:         328
        .size:           8
        .value_kind:     hidden_global_offset_y
      - .offset:         336
        .size:           8
        .value_kind:     hidden_global_offset_z
      - .offset:         344
        .size:           2
        .value_kind:     hidden_grid_dims
      - .offset:         368
        .size:           8
        .value_kind:     hidden_multigrid_sync_arg
      - .offset:         400
        .size:           4
        .value_kind:     hidden_dynamic_lds_size
    .group_segment_fixed_size: 0
    .kernarg_segment_align: 8
    .kernarg_segment_size: 536
    .language:       OpenCL C
    .language_version:
      - 2
      - 0
    .max_flat_workgroup_size: 512
    .name:           _Z8mega_fwd6Params
    .private_segment_fixed_size: 0
    .sgpr_count:     108
    .sgpr_spill_count: 79
    .symbol:         _Z8mega_fwd6Params.kd
    .uniform_work_group_size: 1
    .uses_dynamic_stack: false
    .vgpr_count:     255
    .vgpr_spill_count: 0
    .wavefront_size: 64
